# attention loop: counted lgkmcnt waits (flat->global loads), per-lane K address/stride preselected before loop, first QK LDS reads hoisted above staging; ret_out G prefetch; W1 epilogue ss hoist; scan
# speedup vs baseline: 1.0133x; 1.0133x over previous
.LBB0_381:
	s_and_b64 s[0:1], s[76:77], exec
	s_cselect_b32 s6, s2, s90
	v_mov_b32_e32 v56, v206
	s_lshl_b32 s68, s6, 8
	v_ashrrev_i32_e32 v60, 6, v56
	v_and_b32_e32 v57, 31, v56
	v_lshl_add_u32 v59, v60, 5, s68
	v_or_b32_e32 v198, v59, v57
	v_ashrrev_i32_e32 v199, 31, v198
	v_lshl_add_u64 v[196:197], s[64:65], 0, v[198:199]
	v_mov_b64_e32 v[2:3], s[16:17]
	v_mad_u64_u32 v[2:3], s[0:1], v196, s89, v[2:3]
	v_bfe_u32 v58, v56, 5, 1
	v_mad_i32_i24 v3, v197, s89, v3
	s_lshl_b32 s0, s82, 1
	s_mov_b32 s1, s55
	v_lshl_add_u64 v[4:5], v[2:3], 0, s[0:1]
	v_lshlrev_b32_e32 v0, 4, v58
	v_lshl_add_u64 v[4:5], v[4:5], 0, v[0:1]
	flat_load_dwordx4 v[48:51], v[4:5]
	flat_load_dwordx4 v[44:47], v[4:5] offset:32
	flat_load_dwordx4 v[36:39], v[4:5] offset:64
	flat_load_dwordx4 v[40:43], v[4:5] offset:96
	v_lshl_add_u64 v[2:3], v[2:3], 0, s[54:55]
	v_lshl_add_u64 v[2:3], v[2:3], 0, v[0:1]
	s_movk_i32 s0, 0x1000
	v_add_co_u32_e32 v32, vcc, s0, v2
	v_mov_b64_e32 v[14:15], s[12:13]
	s_nop 0
	v_addc_co_u32_e32 v33, vcc, 0, v3, vcc
	flat_load_dwordx4 v[52:55], v[4:5] offset:128
	flat_load_dwordx4 v[62:65], v[4:5] offset:160
	flat_load_dwordx4 v[66:69], v[4:5] offset:192
	flat_load_dwordx4 v[70:73], v[4:5] offset:224
	s_nop 0
	flat_load_dwordx4 v[2:5], v[32:33]
	flat_load_dwordx4 v[10:13], v[32:33] offset:32
	flat_load_dwordx4 v[6:9], v[32:33] offset:64
	s_nop 0
	flat_load_dwordx4 v[32:35], v[32:33] offset:96
	s_nop 0
	flat_load_dwordx2 v[14:15], v[14:15] sc1
	s_waitcnt vmcnt(0) lgkmcnt(0)
	v_and_b32_e32 v75, 0xffff0000, v49
	v_and_b32_e32 v79, 0xffff0000, v48
	v_and_b32_e32 v78, 0xffff0000, v50
	v_lshlrev_b32_e32 v74, 16, v49
	v_lshlrev_b32_e32 v77, 16, v48
	v_lshlrev_b32_e32 v76, 16, v50
	v_lshlrev_b32_e32 v90, 16, v36
	v_and_b32_e32 v91, 0xffff0000, v36
	v_lshlrev_b32_e32 v92, 16, v37
	v_and_b32_e32 v93, 0xffff0000, v37
	v_lshlrev_b32_e32 v94, 16, v38
	v_and_b32_e32 v96, 0xffff0000, v38
	v_pk_mov_b32 v[36:37], v[38:39], v[42:43] op_sel:[1,0]
	v_lshlrev_b32_e32 v50, 16, v39
	v_mul_f32_e32 v0, v75, v75
	v_pk_mul_f32 v[38:39], v[78:79], v[78:79]
	v_lshlrev_b32_e32 v61, 16, v41
	v_and_b32_e32 v122, 0xffff0000, v41
	v_lshlrev_b32_e32 v41, 16, v43
	v_lshlrev_b32_e32 v95, 16, v40
	v_and_b32_e32 v97, 0xffff0000, v40
	v_mul_f32_e32 v40, v91, v91
	v_mul_f32_e32 v48, v93, v93
	v_pk_fma_f32 v[98:99], v[74:75], v[74:75], v[0:1] op_sel_hi:[1,1,0]
	v_pk_fma_f32 v[38:39], v[76:77], v[76:77], v[38:39]
	v_mul_f32_e32 v102, v61, v61
	v_mul_f32_e32 v103, v122, v122
	v_pk_fma_f32 v[100:101], v[90:91], v[90:91], v[40:41] op_sel_hi:[1,1,0]
	v_pk_fma_f32 v[48:49], v[92:93], v[92:93], v[48:49] op_sel_hi:[1,1,0]
	v_pk_add_f32 v[98:99], v[38:39], v[98:99] op_sel:[1,0] op_sel_hi:[0,1]
	v_and_b32_e32 v85, 0xffff0000, v45
	v_and_b32_e32 v84, 0xffff0000, v44
	v_lshlrev_b32_e32 v87, 16, v47
	v_lshlrev_b32_e32 v86, 16, v46
	v_and_b32_e32 v89, 0xffff0000, v47
	v_and_b32_e32 v88, 0xffff0000, v46
	v_pk_mul_f32 v[46:47], v[96:97], v[96:97]
	v_mov_b32_e32 v101, v102
	v_mov_b32_e32 v49, v103
	v_pk_add_f32 v[38:39], v[38:39], v[98:99]
	v_and_b32_e32 v99, 0xffff0000, v37
	v_and_b32_e32 v98, 0xffff0000, v36
	v_lshlrev_b32_e32 v80, 16, v51
	v_and_b32_e32 v81, 0xffff0000, v51
	v_lshlrev_b32_e32 v83, 16, v45
	v_lshlrev_b32_e32 v82, 16, v44
	v_and_b32_e32 v123, 0xffff0000, v43
	v_lshlrev_b32_e32 v51, 16, v42
	v_pk_mul_f32 v[42:43], v[84:85], v[84:85]
	v_pk_fma_f32 v[46:47], v[94:95], v[94:95], v[46:47]
	v_pk_add_f32 v[48:49], v[100:101], v[48:49]
	v_pk_mul_f32 v[36:37], v[98:99], v[98:99]
	v_pk_mul_f32 v[44:45], v[88:89], v[88:89]
	v_pk_fma_f32 v[42:43], v[82:83], v[82:83], v[42:43]
	v_pk_add_f32 v[46:47], v[46:47], v[48:49]
	v_pk_fma_f32 v[36:37], v[50:51], v[50:51], v[36:37]
	v_mul_f32_e32 v0, v81, v81
	v_pk_fma_f32 v[44:45], v[86:87], v[86:87], v[44:45]
	v_pk_add_f32 v[42:43], v[42:43], v[42:43] op_sel:[0,1] op_sel_hi:[1,0]
	v_pk_add_f32 v[36:37], v[36:37], v[46:47]
	v_pk_fma_f32 v[46:47], v[80:81], v[80:81], v[0:1] op_sel_hi:[1,1,0]
	v_pk_add_f32 v[42:43], v[44:45], v[42:43]
	v_mov_b32_e32 v40, v46
	v_mov_b32_e32 v48, v38
	v_mov_b32_e32 v49, v41
	v_mul_f32_e32 v104, v123, v123
	v_pk_add_f32 v[38:39], v[46:47], v[38:39]
	v_pk_mul_f32 v[46:47], v[40:41], v[48:49]
	v_pk_add_f32 v[42:43], v[44:45], v[42:43] op_sel:[1,0] op_sel_hi:[0,1]
	v_mov_b32_e32 v39, v47
	v_mov_b32_e32 v43, v104
	v_pk_add_f32 v[38:39], v[38:39], v[42:43]
	v_and_b32_e32 v105, 0xffff0000, v53
	v_and_b32_e32 v104, 0xffff0000, v52
	v_readfirstlane_b32 s0, v14
	v_pk_add_f32 v[100:101], v[38:39], v[36:37]
	v_lshlrev_b32_e32 v103, 16, v53
	v_lshlrev_b32_e32 v102, 16, v52
	v_pk_mul_f32 v[36:37], v[104:105], v[104:105]
	v_readfirstlane_b32 s1, v15
	s_add_u32 s0, s0, s18
	v_pk_fma_f32 v[36:37], v[102:103], v[102:103], v[36:37]
	s_addc_u32 s1, s1, s19
	v_lshlrev_b32_e32 v0, 5, v58
	v_pk_add_f32 v[38:39], v[36:37], v[36:37] op_sel:[0,1] op_sel_hi:[1,0]
	v_mov_b64_e32 v[14:15], s[14:15]
	v_lshl_add_u64 v[36:37], s[0:1], 0, v[0:1]
	flat_load_dwordx2 v[14:15], v[14:15] sc1
	v_lshlrev_b32_e32 v107, 16, v55
	flat_load_dwordx2 v[108:109], v[36:37]
	v_lshlrev_b32_e32 v106, 16, v54
	v_and_b32_e32 v55, 0xffff0000, v55
	v_and_b32_e32 v54, 0xffff0000, v54
	v_pk_mul_f32 v[42:43], v[54:55], v[54:55]
	v_lshlrev_b32_e32 v113, 16, v63
	v_pk_fma_f32 v[42:43], v[106:107], v[106:107], v[42:43]
	v_lshlrev_b32_e32 v112, 16, v62
	v_pk_add_f32 v[38:39], v[42:43], v[38:39]
	v_and_b32_e32 v63, 0xffff0000, v63
	v_and_b32_e32 v62, 0xffff0000, v62
	v_lshlrev_b32_e32 v115, 16, v65
	v_lshlrev_b32_e32 v114, 16, v64
	v_and_b32_e32 v65, 0xffff0000, v65
	v_and_b32_e32 v64, 0xffff0000, v64
	v_and_b32_e32 v121, 0xffff0000, v66
	v_pk_add_f32 v[110:111], v[42:43], v[38:39] op_sel:[1,0] op_sel_hi:[0,1]
	v_pk_mul_f32 v[38:39], v[62:63], v[62:63]
	v_pk_mul_f32 v[42:43], v[64:65], v[64:65]
	v_lshlrev_b32_e32 v120, 16, v66
	v_and_b32_e32 v53, 0xffff0000, v67
	v_mul_f32_e32 v40, v121, v121
	v_pk_fma_f32 v[38:39], v[112:113], v[112:113], v[38:39]
	v_pk_fma_f32 v[116:117], v[114:115], v[114:115], v[42:43]
	v_lshlrev_b32_e32 v52, 16, v67
	v_lshlrev_b32_e32 v124, 16, v71
	v_and_b32_e32 v125, 0xffff0000, v71
	v_pk_fma_f32 v[42:43], v[120:121], v[120:121], v[40:41] op_sel_hi:[1,1,0]
	v_mul_f32_e32 v40, v53, v53
	v_pk_add_f32 v[38:39], v[38:39], v[38:39] op_sel:[0,1] op_sel_hi:[1,0]
	v_mul_f32_e32 v46, v124, v124
	v_mul_f32_e32 v71, v125, v125
	v_and_b32_e32 v45, 0xffff0000, v70
	v_and_b32_e32 v44, 0xffff0000, v68
	v_pk_fma_f32 v[66:67], v[52:53], v[52:53], v[40:41] op_sel_hi:[1,1,0]
	v_pk_add_f32 v[118:119], v[116:117], v[38:39]
	v_lshlrev_b32_e32 v49, 16, v70
	v_lshlrev_b32_e32 v48, 16, v68
	v_pk_mul_f32 v[38:39], v[44:45], v[44:45]
	v_mov_b32_e32 v43, v46
	v_mov_b32_e32 v67, v71
	v_pk_fma_f32 v[38:39], v[48:49], v[48:49], v[38:39]
	v_pk_add_f32 v[42:43], v[42:43], v[66:67]
	v_lshlrev_b32_e32 v47, 16, v73
	v_pk_add_f32 v[66:67], v[38:39], v[42:43]
	v_pk_mov_b32 v[38:39], v[68:69], v[72:73] op_sel:[1,0]
	v_lshlrev_b32_e32 v43, 16, v72
	v_and_b32_e32 v39, 0xffff0000, v39
	v_and_b32_e32 v38, 0xffff0000, v38
	v_lshlrev_b32_e32 v42, 16, v69
	v_pk_mul_f32 v[68:69], v[38:39], v[38:39]
	v_mov_b32_e32 v70, v110
	v_pk_fma_f32 v[68:69], v[42:43], v[42:43], v[68:69]
	v_mov_b32_e32 v71, v47
	v_pk_add_f32 v[66:67], v[68:69], v[66:67]
	v_pk_add_f32 v[68:69], v[100:101], v[100:101] op_sel:[0,1] op_sel_hi:[1,0]
	v_and_b32_e32 v126, 0xffff0000, v73
	v_mov_b32_e32 v46, v68
	v_pk_add_f32 v[68:69], v[68:69], v[110:111]
	v_pk_mul_f32 v[70:71], v[46:47], v[70:71]
	v_mul_f32_e32 v127, v126, v126
	v_mov_b32_e32 v69, v71
	v_pk_add_f32 v[70:71], v[116:117], v[118:119] op_sel:[1,0] op_sel_hi:[0,1]
	v_mov_b32_e32 v71, v127
	v_pk_add_f32 v[68:69], v[68:69], v[70:71]
	s_waitcnt vmcnt(0) lgkmcnt(0)
	v_readfirstlane_b32 s0, v14
	v_pk_add_f32 v[66:67], v[68:69], v[66:67]
	v_readfirstlane_b32 s1, v15
	v_pk_add_f32 v[66:67], v[66:67], v[66:67] op_sel:[0,1] op_sel_hi:[1,0]
	s_add_u32 s0, s0, s40
	v_mov_b32_e32 v40, v66
	s_nop 1
	v_permlane32_swap_b32_e32 v66, v40
	v_add_f32_e32 v40, v66, v40
	v_fmamk_f32 v40, v40, 0x3c000000, v207
	v_mul_f32_e32 v46, 0x4b800000, v40
	v_cmp_gt_f32_e32 vcc, s87, v40
	s_addc_u32 s1, s1, s41
	v_lshlrev_b32_e32 v15, 16, v13
	v_cndmask_b32_e32 v40, v40, v46, vcc
	v_rsq_f32_e32 v40, v40
	v_lshlrev_b32_e32 v14, 16, v35
	v_mul_f32_e32 v46, 0x45800000, v40
	v_cndmask_b32_e32 v40, v40, v46, vcc
	v_mul_f32_e32 v68, 0x3dd53b94, v40
	v_mul_f32_e32 v40, v68, v77
	v_mul_f32_e32 v46, v68, v79
	v_mul_f32_e32 v40, v108, v40
	v_mul_f32_e32 v46, v109, v46
	v_cvt_pk_bf16_f32 v128, v40, v46
	flat_load_dwordx2 v[66:67], v[36:37] offset:8
	v_mul_f32_e32 v40, v68, v74
	v_mul_f32_e32 v46, v68, v75
	v_mul_f32_e32 v44, v68, v44
	v_mul_f32_e32 v42, v68, v42
	v_mul_f32_e32 v38, v68, v38
	v_mul_f32_e32 v39, v68, v39
	s_waitcnt vmcnt(0) lgkmcnt(0)
	v_mul_f32_e32 v40, v66, v40
	v_mul_f32_e32 v46, v67, v46
	v_cvt_pk_bf16_f32 v129, v40, v46
	flat_load_dwordx2 v[66:67], v[36:37] offset:16
	v_mul_f32_e32 v40, v68, v76
	v_mul_f32_e32 v46, v68, v78
	s_waitcnt vmcnt(0) lgkmcnt(0)
	v_mul_f32_e32 v40, v40, v66
	v_mul_f32_e32 v46, v46, v67
	v_cvt_pk_bf16_f32 v130, v40, v46
	flat_load_dwordx2 v[66:67], v[36:37] offset:24
	v_mul_f32_e32 v40, v68, v80
	v_mul_f32_e32 v46, v68, v81
	s_waitcnt vmcnt(0) lgkmcnt(0)
	v_mul_f32_e32 v40, v40, v66
	v_mul_f32_e32 v46, v46, v67
	v_cvt_pk_bf16_f32 v131, v40, v46
	flat_load_dwordx2 v[66:67], v[36:37] offset:64
	v_mul_f32_e32 v40, v68, v82
	v_mul_f32_e32 v46, v68, v84
	v_lshlrev_b32_e32 v82, 16, v8
	v_and_b32_e32 v84, 0xffff0000, v8
	v_mov_b32_e32 v162, v84
	v_mov_b32_e32 v160, v82
	s_waitcnt vmcnt(0) lgkmcnt(0)
	v_mul_f32_e32 v40, v40, v66
	v_mul_f32_e32 v46, v46, v67
	v_cvt_pk_bf16_f32 v132, v40, v46
	flat_load_dwordx2 v[66:67], v[36:37] offset:72
	v_mul_f32_e32 v40, v68, v83
	v_mul_f32_e32 v46, v68, v85
	v_lshlrev_b32_e32 v83, 16, v4
	v_and_b32_e32 v85, 0xffff0000, v4
	v_mov_b32_e32 v111, v83
	s_waitcnt vmcnt(0) lgkmcnt(0)
	v_mul_f32_e32 v40, v40, v66
	v_mul_f32_e32 v46, v46, v67
	v_cvt_pk_bf16_f32 v133, v40, v46
	flat_load_dwordx2 v[66:67], v[36:37] offset:80
	v_mul_f32_e32 v40, v68, v86
	v_mul_f32_e32 v46, v68, v88
	v_lshlrev_b32_e32 v86, 16, v7
	v_and_b32_e32 v88, 0xffff0000, v7
	s_waitcnt vmcnt(0) lgkmcnt(0)
	v_mul_f32_e32 v40, v40, v66
	v_mul_f32_e32 v46, v46, v67
	v_cvt_pk_bf16_f32 v134, v40, v46
	flat_load_dwordx2 v[66:67], v[36:37] offset:88
	v_mul_f32_e32 v40, v68, v87
	v_mul_f32_e32 v46, v68, v89
	v_lshlrev_b32_e32 v87, 16, v3
	v_and_b32_e32 v89, 0xffff0000, v3
	v_mov_b32_e32 v119, v87
	s_waitcnt vmcnt(0) lgkmcnt(0)
	v_mul_f32_e32 v40, v40, v66
	v_mul_f32_e32 v46, v46, v67
	v_cvt_pk_bf16_f32 v135, v40, v46
	flat_load_dwordx2 v[66:67], v[36:37] offset:128
	v_mul_f32_e32 v40, v68, v90
	v_mul_f32_e32 v46, v68, v91
	v_lshlrev_b32_e32 v91, 16, v2
	v_lshlrev_b32_e32 v90, 16, v6
	v_mov_b32_e32 v116, v90
	v_mov_b32_e32 v118, v91
	s_waitcnt vmcnt(0) lgkmcnt(0)
	v_mul_f32_e32 v40, v40, v66
	v_mul_f32_e32 v46, v46, v67
	v_cvt_pk_bf16_f32 v136, v40, v46
	flat_load_dwordx2 v[66:67], v[36:37] offset:136
	v_mul_f32_e32 v40, v68, v92
	v_mul_f32_e32 v46, v68, v93
	v_and_b32_e32 v93, 0xffff0000, v2
	v_mul_f32_e32 v2, v68, v126
	v_and_b32_e32 v92, 0xffff0000, v6
	v_mov_b32_e32 v117, v92
	s_waitcnt vmcnt(0) lgkmcnt(0)
	v_mul_f32_e32 v40, v40, v66
	v_mul_f32_e32 v46, v46, v67
	v_cvt_pk_bf16_f32 v137, v40, v46
	flat_load_dwordx2 v[66:67], v[36:37] offset:144
	v_mul_f32_e32 v40, v68, v94
	v_mul_f32_e32 v46, v68, v96
	s_waitcnt vmcnt(0) lgkmcnt(0)
	v_mul_f32_e32 v40, v40, v66
	v_mul_f32_e32 v46, v46, v67
	v_cvt_pk_bf16_f32 v138, v40, v46
	flat_load_dwordx2 v[66:67], v[36:37] offset:152
	v_mul_f32_e32 v40, v68, v50
	v_mul_f32_e32 v46, v68, v98
	v_mov_b32_e32 v98, v15
	s_waitcnt vmcnt(0) lgkmcnt(0)
	v_mul_f32_e32 v40, v40, v66
	v_mul_f32_e32 v46, v46, v67
	v_cvt_pk_bf16_f32 v139, v40, v46
	flat_load_dwordx2 v[66:67], v[36:37] offset:192
	v_mul_f32_e32 v40, v68, v95
	v_mul_f32_e32 v46, v68, v97
	v_pk_mul_f32 v[94:95], v[14:15], v[14:15]
	s_waitcnt vmcnt(0) lgkmcnt(0)
	v_mul_f32_e32 v40, v40, v66
	v_mul_f32_e32 v46, v46, v67
	v_cvt_pk_bf16_f32 v140, v40, v46
	flat_load_dwordx2 v[66:67], v[36:37] offset:200
	v_mul_f32_e32 v40, v68, v61
	v_mul_f32_e32 v46, v68, v122
	v_mul_f32_e32 v122, v92, v92
	v_pk_fma_f32 v[116:117], v[116:117], v[116:117], v[122:123] op_sel_hi:[1,1,0]
	s_waitcnt vmcnt(0) lgkmcnt(0)
	v_mul_f32_e32 v40, v40, v66
	v_mul_f32_e32 v46, v46, v67
	v_cvt_pk_bf16_f32 v141, v40, v46
	flat_load_dwordx2 v[66:67], v[36:37] offset:208
	v_mul_f32_e32 v40, v68, v51
	v_mul_f32_e32 v46, v68, v99
	s_waitcnt vmcnt(0) lgkmcnt(0)
	v_mul_f32_e32 v40, v40, v66
	v_mul_f32_e32 v46, v46, v67
	v_cvt_pk_bf16_f32 v142, v40, v46
	flat_load_dwordx2 v[50:51], v[36:37] offset:216
	v_mul_f32_e32 v40, v68, v41
	v_mul_f32_e32 v41, v68, v123
	v_mul_f32_e32 v46, v68, v102
	s_waitcnt vmcnt(0) lgkmcnt(0)
	v_mul_f32_e32 v40, v40, v50
	v_mul_f32_e32 v41, v41, v51
	v_cvt_pk_bf16_f32 v143, v40, v41
	flat_load_dwordx2 v[40:41], v[36:37] offset:256
	v_mul_f32_e32 v50, v68, v104
	s_waitcnt vmcnt(0) lgkmcnt(0)
	v_mul_f32_e32 v40, v46, v40
	v_mul_f32_e32 v41, v50, v41
	v_cvt_pk_bf16_f32 v144, v40, v41
	flat_load_dwordx2 v[40:41], v[36:37] offset:264
	v_mul_f32_e32 v46, v68, v103
	v_mul_f32_e32 v50, v68, v105
	s_waitcnt vmcnt(0) lgkmcnt(0)
	v_mul_f32_e32 v40, v46, v40
	v_mul_f32_e32 v41, v50, v41
	v_cvt_pk_bf16_f32 v145, v40, v41
	flat_load_dwordx2 v[40:41], v[36:37] offset:272
	v_mul_f32_e32 v46, v68, v106
	v_mul_f32_e32 v50, v68, v54
	v_lshlrev_b32_e32 v54, 16, v9
	s_waitcnt vmcnt(0) lgkmcnt(0)
	v_mul_f32_e32 v40, v46, v40
	v_mul_f32_e32 v41, v50, v41
	v_cvt_pk_bf16_f32 v146, v40, v41
	flat_load_dwordx2 v[40:41], v[36:37] offset:280
	v_mul_f32_e32 v46, v68, v107
	v_mul_f32_e32 v50, v68, v55
	v_lshlrev_b32_e32 v55, 16, v5
	v_mov_b32_e32 v110, v55
	s_waitcnt vmcnt(0) lgkmcnt(0)
	v_mul_f32_e32 v40, v46, v40
	v_mul_f32_e32 v41, v50, v41
	v_cvt_pk_bf16_f32 v147, v40, v41
	flat_load_dwordx2 v[40:41], v[36:37] offset:320
	v_mul_f32_e32 v46, v68, v112
	v_mul_f32_e32 v50, v68, v62
	s_waitcnt vmcnt(0) lgkmcnt(0)
	v_mul_f32_e32 v40, v46, v40
	v_mul_f32_e32 v41, v50, v41
	v_cvt_pk_bf16_f32 v148, v40, v41
	flat_load_dwordx2 v[40:41], v[36:37] offset:328
	v_mul_f32_e32 v46, v68, v113
	v_mul_f32_e32 v50, v68, v63
	v_mov_b32_e32 v113, v85
	s_waitcnt vmcnt(0) lgkmcnt(0)
	v_mul_f32_e32 v40, v46, v40
	v_mul_f32_e32 v41, v50, v41
	v_cvt_pk_bf16_f32 v149, v40, v41
	flat_load_dwordx2 v[40:41], v[36:37] offset:336
	v_mul_f32_e32 v46, v68, v114
	v_mul_f32_e32 v50, v68, v64
	v_mov_b32_e32 v114, v86
	s_waitcnt vmcnt(0) lgkmcnt(0)
	v_mul_f32_e32 v40, v46, v40
	v_mul_f32_e32 v41, v50, v41
	v_cvt_pk_bf16_f32 v150, v40, v41
	flat_load_dwordx2 v[40:41], v[36:37] offset:344
	v_mul_f32_e32 v46, v68, v115
	v_mul_f32_e32 v50, v68, v65
	v_mov_b32_e32 v115, v88
	s_waitcnt vmcnt(0) lgkmcnt(0)
	v_mul_f32_e32 v40, v46, v40
	v_mul_f32_e32 v41, v50, v41
	v_cvt_pk_bf16_f32 v151, v40, v41
	flat_load_dwordx2 v[40:41], v[36:37] offset:384
	v_mul_f32_e32 v46, v68, v120
	v_mul_f32_e32 v50, v68, v121
	v_mov_b32_e32 v120, v93
	v_mov_b32_e32 v121, v89
	v_pk_mul_f32 v[120:121], v[120:121], v[120:121]
	s_waitcnt vmcnt(0) lgkmcnt(0)
	v_mul_f32_e32 v40, v46, v40
	v_mul_f32_e32 v41, v50, v41
	v_cvt_pk_bf16_f32 v152, v40, v41
	flat_load_dwordx2 v[40:41], v[36:37] offset:392
	v_mul_f32_e32 v46, v68, v52
	v_mul_f32_e32 v50, v68, v53
	v_and_b32_e32 v53, 0xffff0000, v5
	v_and_b32_e32 v52, 0xffff0000, v9
	v_mov_b32_e32 v112, v53
	v_pk_mul_f32 v[112:113], v[112:113], v[112:113]
	v_mov_b32_e32 v126, v52
	s_waitcnt vmcnt(0) lgkmcnt(0)
	v_mul_f32_e32 v40, v46, v40
	v_mul_f32_e32 v41, v50, v41
	v_cvt_pk_bf16_f32 v153, v40, v41
	flat_load_dwordx2 v[40:41], v[36:37] offset:400
	v_mul_f32_e32 v46, v68, v48
	v_lshlrev_b64 v[50:51], 5, v[196:197]
	s_waitcnt vmcnt(0) lgkmcnt(0)
	v_mul_f32_e32 v40, v46, v40
	v_mul_f32_e32 v41, v44, v41
	v_cvt_pk_bf16_f32 v154, v40, v41
	flat_load_dwordx2 v[40:41], v[36:37] offset:408
	v_lshlrev_b32_e32 v46, 3, v58
	v_or_b32_e32 v50, v50, v46
	v_lshlrev_b32_e32 v44, 16, v32
	v_and_b32_e32 v32, 0xffff0000, v32
	v_mov_b32_e32 v163, v32
	v_mov_b32_e32 v161, v44
	s_waitcnt vmcnt(0) lgkmcnt(0)
	v_mul_f32_e32 v40, v42, v40
	v_mul_f32_e32 v38, v38, v41
	v_cvt_pk_bf16_f32 v155, v40, v38
	flat_load_dwordx2 v[40:41], v[36:37] offset:448
	v_mul_f32_e32 v38, v68, v49
	v_mul_f32_e32 v42, v68, v45
	v_lshl_add_u64 v[48:49], s[0:1], 0, v[0:1]
	v_mul_f32_e32 v0, v68, v47
	v_lshlrev_b32_e32 v45, 16, v10
	v_mov_b32_e32 v106, v45
	s_waitcnt vmcnt(0) lgkmcnt(0)
	v_mul_f32_e32 v38, v38, v40
	v_mul_f32_e32 v40, v42, v41
	v_cvt_pk_bf16_f32 v156, v38, v40
	flat_load_dwordx2 v[40:41], v[36:37] offset:456
	v_mul_f32_e32 v38, v68, v124
	v_mul_f32_e32 v42, v68, v125
	v_mov_b32_e32 v124, v54
	s_waitcnt vmcnt(0) lgkmcnt(0)
	v_mul_f32_e32 v38, v38, v40
	v_mul_f32_e32 v40, v42, v41
	v_cvt_pk_bf16_f32 v157, v38, v40
	flat_load_dwordx2 v[40:41], v[36:37] offset:464
	v_mul_f32_e32 v38, v68, v43
	v_and_b32_e32 v43, 0xffff0000, v11
	v_and_b32_e32 v42, 0xffff0000, v33
	v_mov_b32_e32 v109, v43
	v_pk_mul_f32 v[104:105], v[42:43], v[42:43]
	s_waitcnt vmcnt(0) lgkmcnt(0)
	v_mul_f32_e32 v38, v38, v40
	v_mul_f32_e32 v39, v39, v41
	v_cvt_pk_bf16_f32 v158, v38, v39
	flat_load_dwordx2 v[62:63], v[36:37] offset:472
	v_lshlrev_b64 v[36:37], 2, v[50:51]
	v_lshl_add_u64 v[74:75], s[46:47], 0, v[36:37]
	v_lshl_add_u64 v[78:79], s[48:49], 0, v[36:37]
	v_or_b32_e32 v36, 16, v36
	v_lshl_add_u64 v[76:77], s[46:47], 0, v[36:37]
	v_lshl_add_u64 v[80:81], s[48:49], 0, v[36:37]
	v_and_b32_e32 v37, 0xffff0000, v13
	v_and_b32_e32 v36, 0xffff0000, v35
	v_lshlrev_b32_e32 v39, 16, v12
	v_and_b32_e32 v35, 0xffff0000, v12
	v_lshlrev_b32_e32 v41, 16, v11
	v_lshlrev_b32_e32 v40, 16, v33
	v_and_b32_e32 v33, 0xffff0000, v10
	v_mov_b32_e32 v100, v37
	v_mov_b32_e32 v101, v35
	v_mov_b32_e32 v108, v33
	v_mov_b32_e32 v99, v39
	v_mov_b32_e32 v107, v41
	v_pk_mul_f32 v[100:101], v[100:101], v[100:101]
	v_pk_mul_f32 v[108:109], v[108:109], v[108:109]
	v_lshlrev_b32_e32 v38, 16, v34
	v_and_b32_e32 v34, 0xffff0000, v34
	v_pk_mul_f32 v[102:103], v[40:41], v[40:41]
	v_pk_fma_f32 v[98:99], v[98:99], v[98:99], v[100:101]
	v_pk_fma_f32 v[100:101], v[106:107], v[106:107], v[108:109]
	v_pk_fma_f32 v[108:109], v[118:119], v[118:119], v[120:121]
	v_mov_b32_e32 v127, v34
	v_pk_fma_f32 v[106:107], v[110:111], v[110:111], v[112:113]
	v_mov_b32_e32 v117, v102
	v_pk_add_f32 v[100:101], v[100:101], v[100:101] op_sel:[0,1] op_sel_hi:[1,0]
	v_pk_add_f32 v[102:103], v[108:109], v[108:109] op_sel:[0,1] op_sel_hi:[1,0]
	v_pk_mul_f32 v[122:123], v[126:127], v[126:127]
	v_pk_mul_f32 v[126:127], v[162:163], v[162:163]
	v_pk_add_f32 v[100:101], v[98:99], v[100:101] op_sel:[1,0] op_sel_hi:[0,1]
	v_pk_add_f32 v[102:103], v[106:107], v[102:103] op_sel:[1,0] op_sel_hi:[0,1]
	v_pk_mul_f32 v[96:97], v[36:37], v[36:37]
	v_mov_b32_e32 v125, v38
	v_pk_fma_f32 v[112:113], v[160:161], v[160:161], v[126:127]
	v_pk_add_f32 v[98:99], v[98:99], v[100:101]
	v_pk_add_f32 v[100:101], v[106:107], v[102:103]
	v_pk_fma_f32 v[110:111], v[124:125], v[124:125], v[122:123]
	v_mov_b32_e32 v101, v94
	v_mov_b32_e32 v99, v96
	v_pk_add_f32 v[94:95], v[100:101], v[98:99]
	v_or_b32_e32 v50, 16, v50
	s_waitcnt vmcnt(0) lgkmcnt(0)
	v_mul_f32_e32 v2, v2, v63
	v_mul_f32_e32 v0, v0, v62
	v_cvt_pk_bf16_f32 v159, v0, v2
	flat_load_dwordx4 v[62:65], v[48:49] offset:128
	flat_load_dwordx4 v[66:69], v[48:49] offset:144
	flat_load_dwordx4 v[70:73], v[48:49]
	flat_load_dwordx4 v[10:13], v[48:49] offset:16
	flat_load_dwordx4 v[6:9], v[76:77]
	flat_load_dwordx4 v[2:5], v[80:81]
	s_nop 0
	flat_load_dwordx4 v[74:77], v[74:75]
	s_nop 0
	flat_load_dwordx4 v[78:81], v[78:79]
	v_mul_f32_e32 v0, v88, v88
	v_pk_fma_f32 v[114:115], v[114:115], v[114:115], v[0:1] op_sel_hi:[1,1,0]
	s_waitcnt vmcnt(0) lgkmcnt(0)
	v_mov_b32_e32 v106, v64
	v_mov_b32_e32 v115, v104
	v_pk_add_f32 v[104:105], v[116:117], v[114:115]
	v_mov_b32_e32 v98, v68
	v_pk_add_f32 v[104:105], v[112:113], v[104:105]
	v_mov_b32_e32 v99, v12
	v_pk_add_f32 v[102:103], v[110:111], v[104:105]
	v_mov_b32_e32 v107, v72
	v_pk_add_f32 v[94:95], v[94:95], v[102:103]
	v_mov_b32_e32 v102, v66
	v_pk_add_f32 v[94:95], v[94:95], v[94:95] op_sel:[0,1] op_sel_hi:[1,0]
	v_mov_b32_e32 v103, v10
	v_mov_b32_e32 v0, v94
	s_nop 1
	v_permlane32_swap_b32_e32 v94, v0
	v_add_f32_e32 v0, v94, v0
	v_fmamk_f32 v0, v0, 0x3c800000, v207
	v_mul_f32_e32 v47, 0x4b800000, v0
	v_cmp_gt_f32_e32 vcc, s87, v0
	v_mov_b32_e32 v110, v62
	v_mov_b32_e32 v111, v70
	v_cndmask_b32_e32 v0, v0, v47, vcc
	v_rsq_f32_e32 v0, v0
	v_mov_b32_e32 v70, v63
	v_mov_b32_e32 v72, v65
	v_mov_b32_e32 v10, v67
	v_mul_f32_e32 v47, 0x45800000, v0
	v_cndmask_b32_e32 v0, v0, v47, vcc
	v_pk_mul_f32 v[90:91], v[0:1], v[90:91] op_sel_hi:[0,1]
	v_pk_mul_f32 v[92:93], v[0:1], v[92:93] op_sel_hi:[0,1]
	v_pk_mul_f32 v[86:87], v[0:1], v[86:87] op_sel_hi:[0,1]
	v_pk_mul_f32 v[88:89], v[0:1], v[88:89] op_sel_hi:[0,1]
	v_pk_mul_f32 v[82:83], v[0:1], v[82:83] op_sel_hi:[0,1]
	v_pk_mul_f32 v[84:85], v[0:1], v[84:85] op_sel_hi:[0,1]
	v_pk_mul_f32 v[54:55], v[0:1], v[54:55] op_sel_hi:[0,1]
	v_pk_mul_f32 v[52:53], v[0:1], v[52:53] op_sel_hi:[0,1]
	v_mov_b32_e32 v12, v69
	v_mov_b32_e32 v100, v8
	v_mov_b32_e32 v101, v4
	v_mov_b32_e32 v104, v6
	v_mov_b32_e32 v105, v2
	v_mov_b32_e32 v108, v76
	v_mov_b32_e32 v109, v80
	v_mov_b32_e32 v112, v74
	v_mov_b32_e32 v113, v78
	v_mov_b32_e32 v114, v78
	v_mov_b32_e32 v115, v74
	v_mov_b32_e32 v74, v79
	v_mov_b32_e32 v78, v75
	v_mov_b32_e32 v62, v80
	v_mov_b32_e32 v63, v76
	v_mov_b32_e32 v76, v81
	v_mov_b32_e32 v80, v77
	v_mov_b32_e32 v64, v2
	v_mov_b32_e32 v65, v6
	v_mov_b32_e32 v6, v3
	v_mov_b32_e32 v2, v7
	v_mov_b32_e32 v66, v4
	v_mov_b32_e32 v67, v8
	v_mov_b32_e32 v8, v5
	v_pk_mul_f32 v[68:69], v[90:91], v[110:111]
	v_pk_mul_f32 v[70:71], v[92:93], v[70:71]
	v_pk_mul_f32 v[86:87], v[86:87], v[106:107]
	v_pk_mul_f32 v[72:73], v[88:89], v[72:73]
	v_pk_mul_f32 v[82:83], v[82:83], v[102:103]
	v_pk_mul_f32 v[10:11], v[84:85], v[10:11]
	v_pk_mul_f32 v[54:55], v[54:55], v[98:99]
	v_pk_mul_f32 v[12:13], v[52:53], v[12:13]
	v_mov_b32_e32 v4, v9
	v_pk_mul_f32 v[52:53], v[68:69], v[114:115]
	v_pk_mul_f32 v[68:69], v[68:69], v[112:113]
	v_pk_mul_f32 v[74:75], v[70:71], v[74:75]
	v_pk_mul_f32 v[70:71], v[70:71], v[78:79]
	v_pk_mul_f32 v[62:63], v[86:87], v[62:63]
	v_pk_mul_f32 v[78:79], v[86:87], v[108:109]
	v_pk_mul_f32 v[76:77], v[72:73], v[76:77]
	v_pk_mul_f32 v[72:73], v[72:73], v[80:81]
	v_pk_mul_f32 v[64:65], v[82:83], v[64:65]
	v_pk_mul_f32 v[6:7], v[10:11], v[6:7]
	v_pk_mul_f32 v[2:3], v[10:11], v[2:3]
	v_pk_mul_f32 v[10:11], v[54:55], v[66:67]
	v_pk_mul_f32 v[54:55], v[54:55], v[100:101]
	v_pk_mul_f32 v[8:9], v[12:13], v[8:9]
	v_lshlrev_b64 v[94:95], 2, v[50:51]
	v_pk_mul_f32 v[80:81], v[82:83], v[104:105]
	v_pk_mul_f32 v[4:5], v[12:13], v[4:5]
	v_sub_f32_e32 v12, v53, v52
	v_add_f32_e32 v13, v68, v69
	v_sub_f32_e32 v47, v75, v74
	v_add_f32_e32 v52, v70, v71
	v_sub_f32_e32 v53, v63, v62
	v_add_f32_e32 v61, v78, v79
	v_add_f32_e32 v63, v72, v73
	v_sub_f32_e32 v64, v65, v64
	v_sub_f32_e32 v6, v7, v6
	v_add_f32_e32 v7, v54, v55
	v_sub_f32_e32 v8, v9, v8
	v_lshl_add_u64 v[50:51], s[48:49], 0, v[94:95]
	v_sub_f32_e32 v62, v77, v76
	v_add_f32_e32 v65, v80, v81
	v_add_f32_e32 v2, v2, v3
	v_sub_f32_e32 v3, v11, v10
	v_add_f32_e32 v4, v4, v5
	v_mul_f32_e32 v5, 0x3dd53b94, v12
	v_mul_f32_e32 v9, 0x3dd53b94, v13
	v_mul_f32_e32 v10, 0x3dd53b94, v47
	v_mul_f32_e32 v11, 0x3dd53b94, v52
	v_mul_f32_e32 v12, 0x3dd53b94, v53
	v_mul_f32_e32 v13, 0x3dd53b94, v61
	v_mul_f32_e32 v52, 0x3dd53b94, v63
	v_mul_f32_e32 v53, 0x3dd53b94, v64
	v_mul_f32_e32 v6, 0x3dd53b94, v6
	v_mul_f32_e32 v7, 0x3dd53b94, v7
	v_mul_f32_e32 v8, 0x3dd53b94, v8
	v_lshl_add_u64 v[96:97], s[46:47], 0, v[94:95]
	v_mul_f32_e32 v47, 0x3dd53b94, v62
	v_mul_f32_e32 v54, 0x3dd53b94, v65
	v_mul_f32_e32 v2, 0x3dd53b94, v2
	v_mul_f32_e32 v3, 0x3dd53b94, v3
	v_mul_f32_e32 v4, 0x3dd53b94, v4
	v_cvt_pk_bf16_f32 v160, v5, v10
	v_cvt_pk_bf16_f32 v161, v12, v47
	v_cvt_pk_bf16_f32 v162, v53, v6
	v_cvt_pk_bf16_f32 v163, v3, v8
	v_cvt_pk_bf16_f32 v164, v9, v11
	v_cvt_pk_bf16_f32 v165, v13, v52
	v_cvt_pk_bf16_f32 v166, v54, v2
	v_cvt_pk_bf16_f32 v167, v7, v4
	flat_load_dwordx4 v[6:9], v[48:49] offset:192
	flat_load_dwordx4 v[10:13], v[48:49] offset:64
	s_nop 0
	flat_load_dwordx4 v[50:53], v[50:51]
	s_nop 0
	flat_load_dwordx4 v[62:65], v[96:97]
	v_or_b32_e32 v94, 16, v94
	v_lshl_add_u64 v[2:3], s[46:47], 0, v[94:95]
	v_lshl_add_u64 v[4:5], s[48:49], 0, v[94:95]
	flat_load_dwordx4 v[66:69], v[48:49] offset:208
	flat_load_dwordx4 v[70:73], v[48:49] offset:80
	flat_load_dwordx4 v[74:77], v[4:5]
	flat_load_dwordx4 v[78:81], v[2:3]
	v_mul_hi_i32 v2, v56, s81
	v_lshrrev_b32_e32 v3, 31, v2
	v_ashrrev_i32_e32 v2, 2, v2
	v_pk_mul_f32 v[44:45], v[0:1], v[44:45] op_sel_hi:[0,1]
	v_add_u32_e32 v3, v2, v3
	v_pk_mul_f32 v[32:33], v[0:1], v[32:33] op_sel_hi:[0,1]
	v_pk_mul_f32 v[40:41], v[0:1], v[40:41] op_sel_hi:[0,1]
	v_pk_mul_f32 v[42:43], v[0:1], v[42:43] op_sel_hi:[0,1]
	v_pk_mul_f32 v[38:39], v[0:1], v[38:39] op_sel_hi:[0,1]
	v_pk_mul_f32 v[34:35], v[0:1], v[34:35] op_sel_hi:[0,1]
	v_pk_mul_f32 v[14:15], v[0:1], v[14:15] op_sel_hi:[0,1]
	v_pk_mul_f32 v[36:37], v[0:1], v[36:37] op_sel_hi:[0,1]
	v_mul_lo_u32 v2, v3, 24
	v_sub_u32_e32 v2, v56, v2
	v_lshlrev_b32_e32 v5, 3, v2
	v_cmp_lt_i32_e32 vcc, 15, v2
	s_waitcnt vmcnt(0) lgkmcnt(0)
	v_mov_b32_e32 v48, v6
	v_mov_b32_e32 v49, v10
	v_mov_b32_e32 v54, v50
	v_mov_b32_e32 v55, v62
	v_mov_b32_e32 v10, v7
	v_mov_b32_e32 v6, v8
	v_mov_b32_e32 v7, v12
	v_mov_b32_e32 v12, v9
	v_mov_b32_e32 v8, v66
	v_mov_b32_e32 v9, v70
	v_mov_b32_e32 v70, v67
	v_mov_b32_e32 v66, v68
	v_mov_b32_e32 v67, v72
	v_mov_b32_e32 v72, v69
	v_pk_mul_f32 v[44:45], v[44:45], v[48:49]
	v_mov_b32_e32 v82, v62
	v_mov_b32_e32 v83, v50
	v_mov_b32_e32 v62, v51
	v_mov_b32_e32 v50, v63
	v_mov_b32_e32 v84, v52
	v_mov_b32_e32 v85, v64
	v_mov_b32_e32 v86, v64
	v_mov_b32_e32 v87, v52
	v_mov_b32_e32 v64, v53
	v_mov_b32_e32 v52, v65
	v_mov_b32_e32 v88, v74
	v_mov_b32_e32 v89, v78
	v_mov_b32_e32 v90, v78
	v_mov_b32_e32 v91, v74
	v_mov_b32_e32 v78, v75
	v_mov_b32_e32 v74, v79
	v_mov_b32_e32 v92, v76
	v_mov_b32_e32 v93, v80
	v_mov_b32_e32 v94, v80
	v_mov_b32_e32 v95, v76
	v_mov_b32_e32 v80, v77
	v_mov_b32_e32 v76, v81
	v_pk_mul_f32 v[10:11], v[32:33], v[10:11]
	v_pk_mul_f32 v[6:7], v[40:41], v[6:7]
	v_pk_mul_f32 v[12:13], v[42:43], v[12:13]
	v_pk_mul_f32 v[8:9], v[38:39], v[8:9]
	v_pk_mul_f32 v[32:33], v[34:35], v[70:71]
	v_pk_mul_f32 v[14:15], v[14:15], v[66:67]
	v_pk_mul_f32 v[34:35], v[36:37], v[72:73]
	v_pk_mul_f32 v[36:37], v[44:45], v[54:55]
	v_pk_mul_f32 v[38:39], v[44:45], v[82:83]
	v_pk_mul_f32 v[40:41], v[10:11], v[62:63]
	v_pk_mul_f32 v[10:11], v[10:11], v[50:51]
	v_pk_mul_f32 v[42:43], v[6:7], v[84:85]
	v_pk_mul_f32 v[6:7], v[6:7], v[86:87]
	v_pk_mul_f32 v[44:45], v[12:13], v[64:65]
	v_pk_mul_f32 v[12:13], v[12:13], v[52:53]
	v_pk_mul_f32 v[48:49], v[8:9], v[88:89]
	v_pk_mul_f32 v[8:9], v[8:9], v[90:91]
	v_pk_mul_f32 v[50:51], v[32:33], v[78:79]
	v_pk_mul_f32 v[32:33], v[32:33], v[74:75]
	v_pk_mul_f32 v[52:53], v[14:15], v[92:93]
	v_pk_mul_f32 v[14:15], v[14:15], v[94:95]
	v_pk_mul_f32 v[54:55], v[34:35], v[80:81]
	v_pk_mul_f32 v[34:35], v[34:35], v[76:77]
	v_sub_f32_e32 v0, v37, v36
	v_add_f32_e32 v4, v38, v39
	v_sub_f32_e32 v36, v41, v40
	v_add_f32_e32 v10, v10, v11
	v_sub_f32_e32 v11, v43, v42
	v_add_f32_e32 v6, v6, v7
	v_sub_f32_e32 v7, v45, v44
	v_add_f32_e32 v12, v12, v13
	v_sub_f32_e32 v13, v49, v48
	v_add_f32_e32 v8, v8, v9
	v_sub_f32_e32 v9, v51, v50
	v_add_f32_e32 v32, v32, v33
	v_sub_f32_e32 v33, v53, v52
	v_add_f32_e32 v14, v14, v15
	v_sub_f32_e32 v15, v55, v54
	v_add_f32_e32 v34, v34, v35
	v_mul_f32_e32 v0, 0x3dd53b94, v0
	v_mul_f32_e32 v4, 0x3dd53b94, v4
	v_mul_f32_e32 v35, 0x3dd53b94, v36
	v_mul_f32_e32 v10, 0x3dd53b94, v10
	v_mul_f32_e32 v11, 0x3dd53b94, v11
	v_mul_f32_e32 v6, 0x3dd53b94, v6
	v_mul_f32_e32 v7, 0x3dd53b94, v7
	v_mul_f32_e32 v12, 0x3dd53b94, v12
	v_mul_f32_e32 v13, 0x3dd53b94, v13
	v_mul_f32_e32 v8, 0x3dd53b94, v8
	v_mul_f32_e32 v9, 0x3dd53b94, v9
	v_mul_f32_e32 v32, 0x3dd53b94, v32
	v_mul_f32_e32 v33, 0x3dd53b94, v33
	v_mul_f32_e32 v14, 0x3dd53b94, v14
	v_mul_f32_e32 v15, 0x3dd53b94, v15
	v_mul_f32_e32 v34, 0x3dd53b94, v34
	v_cvt_pk_bf16_f32 v168, v0, v35
	v_cvt_pk_bf16_f32 v169, v11, v7
	v_cvt_pk_bf16_f32 v170, v13, v9
	v_cvt_pk_bf16_f32 v171, v33, v15
	v_cvt_pk_bf16_f32 v172, v4, v10
	v_cvt_pk_bf16_f32 v173, v6, v12
	v_cvt_pk_bf16_f32 v174, v8, v32
	v_cvt_pk_bf16_f32 v175, v14, v34
	s_and_saveexec_b64 s[0:1], vcc
	s_xor_b64 s[0:1], exec, s[0:1]
	v_lshl_add_u32 v0, v3, 6, v5
	v_sub_u32_e32 v0, 0x7f, v0
	s_andn2_saveexec_b64 s[0:1], s[0:1]
	v_lshl_or_b32 v0, v3, 11, s82
	v_add_u32_e32 v0, v0, v5
	s_or_b64 exec, exec, s[0:1]
	v_add_u32_e32 v2, 0x200, v56
	v_mul_hi_i32 v4, v2, s81
	v_lshrrev_b32_e32 v6, 31, v4
	v_ashrrev_i32_e32 v4, 2, v4
	v_add_u32_e32 v6, v4, v6
	v_mul_lo_u32 v4, v6, 24
	v_sub_u32_e32 v2, v2, v4
	v_lshlrev_b32_e32 v7, 3, v2
	v_cmp_lt_i32_e32 vcc, 15, v2
	s_and_saveexec_b64 s[0:1], vcc
	s_xor_b64 s[0:1], exec, s[0:1]
	v_lshl_add_u32 v2, v6, 6, v7
	v_sub_u32_e32 v2, 0x7f, v2
	s_andn2_saveexec_b64 s[0:1], s[0:1]
	v_lshl_or_b32 v2, v6, 11, s82
	v_add_u32_e32 v2, v2, v7
	s_or_b64 exec, exec, s[0:1]
	v_add_u32_e32 v4, 0x400, v56
	v_mul_hi_i32 v8, v4, s81
	v_lshrrev_b32_e32 v9, 31, v8
	v_ashrrev_i32_e32 v8, 2, v8
	v_add_u32_e32 v8, v8, v9
	v_mul_lo_u32 v9, v8, 24
	v_sub_u32_e32 v4, v4, v9
	v_lshlrev_b32_e32 v9, 3, v4
	v_cmp_lt_i32_e32 vcc, 15, v4
	s_and_saveexec_b64 s[0:1], vcc
	s_xor_b64 s[0:1], exec, s[0:1]
	v_lshl_add_u32 v4, v8, 6, v9
	v_sub_u32_e32 v4, 0x7f, v4
	s_andn2_saveexec_b64 s[0:1], s[0:1]
	v_lshl_or_b32 v4, v8, 11, s82
	v_add_u32_e32 v4, v4, v9
	s_or_b64 exec, exec, s[0:1]
	v_mul_lo_u32 v6, v6, s84
	v_add_lshl_u32 v224, v6, v7, 1
	v_not_b32_e32 v6, v0
	v_mov_b32_e32 v7, v1
	v_lshlrev_b64 v[14:15], 1, v[0:1]
	v_lshlrev_b64 v[44:45], 1, v[6:7]
	v_lshl_add_u64 v[10:11], s[4:5], 0, v[14:15]
	v_lshl_add_u64 v[12:13], s[66:67], 0, v[44:45]
	v_cmp_gt_i32_e32 vcc, 0, v0
	v_mul_lo_u32 v3, v3, s84
	v_add_lshl_u32 v225, v3, v5, 1
	v_cndmask_b32_e32 v11, v11, v13, vcc
	v_cndmask_b32_e32 v10, v10, v12, vcc
	flat_load_dwordx4 v[32:35], v[10:11]
	v_mov_b32_e32 v3, v1
	v_not_b32_e32 v10, v2
	v_mov_b32_e32 v11, v1
	v_lshlrev_b64 v[62:63], 1, v[2:3]
	v_lshlrev_b64 v[64:65], 1, v[10:11]
	v_lshl_add_u64 v[12:13], s[4:5], 0, v[62:63]
	v_lshl_add_u64 v[36:37], s[66:67], 0, v[64:65]
	v_cmp_gt_i32_e64 s[36:37], 0, v2
	v_mov_b32_e32 v5, v1
	v_mul_lo_u32 v8, v8, s84
	v_cndmask_b32_e64 v13, v13, v37, s[36:37]
	v_cndmask_b32_e64 v12, v12, v36, s[36:37]
	flat_load_dwordx4 v[36:39], v[12:13]
	v_not_b32_e32 v12, v4
	v_mov_b32_e32 v13, v1
	v_lshlrev_b64 v[66:67], 1, v[4:5]
	v_lshlrev_b64 v[68:69], 1, v[12:13]
	v_add_lshl_u32 v199, v8, v9, 1
	v_ashrrev_i32_e32 v8, 3, v56
	v_lshl_add_u64 v[40:41], s[4:5], 0, v[66:67]
	v_lshl_add_u64 v[42:43], s[66:67], 0, v[68:69]
	v_cmp_gt_i32_e64 s[38:39], 0, v4
	v_add_u32_e32 v48, s82, v8
	v_lshlrev_b32_e32 v9, 4, v56
	v_cndmask_b32_e64 v41, v41, v43, s[38:39]
	v_cndmask_b32_e64 v40, v40, v42, s[38:39]
	flat_load_dwordx4 v[40:43], v[40:41]
	v_and_b32_e32 v70, 0x70, v9
	v_mov_b32_e32 v71, v1
	v_ashrrev_i32_e32 v49, 31, v48
	v_lshl_add_u64 v[52:53], s[56:57], 0, v[70:71]
	v_lshlrev_b64 v[72:73], 15, v[48:49]
	v_lshl_add_u64 v[48:49], v[52:53], 0, v[72:73]
	v_lshl_add_u64 v[74:75], v[72:73], 0, s[22:23]
	flat_load_dwordx4 v[48:51], v[48:49]
	v_lshl_add_u64 v[52:53], v[52:53], 0, v[74:75]
	flat_load_dwordx4 v[52:55], v[52:53]
	v_add_u32_e32 v9, 0, v225
	s_movk_i32 s0, 0x88
	v_lshl_add_u64 v[14:15], s[30:31], 0, v[14:15]
	s_waitcnt vmcnt(0) lgkmcnt(0)
	ds_write_b128 v9, v[32:35]
	v_add_u32_e32 v9, 0, v224
	v_lshl_add_u64 v[32:33], s[50:51], 0, v[44:45]
	v_cndmask_b32_e32 v15, v15, v33, vcc
	v_cndmask_b32_e32 v14, v14, v32, vcc
	v_lshl_add_u64 v[32:33], s[50:51], 0, v[64:65]
	ds_write_b128 v9, v[36:39]
	v_add_u32_e32 v9, 0, v199
	ds_write_b128 v9, v[40:43]
	v_mul_lo_u32 v9, v8, s0
	v_add3_u32 v233, 0, v70, v9
	v_add_u32_e32 v9, 0xc800, v233
	v_cmp_lt_i32_e64 s[0:1], 3, v60
	ds_write2_b64 v9, v[48:49], v[50:51] offset1:1
	v_add_u32_e32 v9, 0xea00, v233
	ds_write2_b64 v9, v[52:53], v[54:55] offset1:1
	flat_load_dwordx4 v[176:179], v[14:15]
	v_lshl_add_u64 v[14:15], s[30:31], 0, v[62:63]
	v_cndmask_b32_e64 v15, v15, v33, s[36:37]
	v_cndmask_b32_e64 v14, v14, v32, s[36:37]
	flat_load_dwordx4 v[180:183], v[14:15]
	v_lshl_add_u64 v[14:15], s[30:31], 0, v[66:67]
	v_lshl_add_u64 v[32:33], s[50:51], 0, v[68:69]
	v_cndmask_b32_e64 v15, v15, v33, s[38:39]
	v_cndmask_b32_e64 v14, v14, v32, s[38:39]
	flat_load_dwordx4 v[184:187], v[14:15]
	v_lshl_add_u64 v[14:15], s[44:45], 0, v[70:71]
	v_lshl_add_u64 v[32:33], v[14:15], 0, v[72:73]
	v_lshl_add_u64 v[14:15], v[14:15], 0, v[74:75]
	v_lshl_add_u64 v[32:33], v[32:33], 0, s[74:75]
	v_lshl_add_u64 v[14:15], v[14:15], 0, s[74:75]
	flat_load_dwordx4 v[188:191], v[32:33]
	flat_load_dwordx4 v[192:195], v[14:15]
	s_and_saveexec_b64 s[78:79], s[0:1]
	s_setprio 1
	s_or_b64 exec, exec, s[78:79]
	s_movk_i32 s0, 0x190
	v_mad_u32_u24 v9, v57, s0, 0
	v_mul_i32_i24_e32 v14, 0xfffffef8, v57
	v_lshl_add_u32 v236, v58, 4, v9
	v_add3_u32 v237, v9, v14, v46
	v_ashrrev_i32_e32 v9, 31, v8
	v_lshlrev_b64 v[14:15], 15, v[8:9]
	v_and_b32_e32 v9, 7, v56
	v_add_u32_e32 v8, s69, v8
	v_lshlrev_b32_e32 v32, 4, v9
	v_ashrrev_i32_e32 v9, 31, v8
	v_lshl_add_u64 v[14:15], s[62:63], 0, v[14:15]
	v_mov_b32_e32 v33, v1
	v_lshlrev_b64 v[8:9], 15, v[8:9]
	v_lshl_add_u64 v[200:201], v[14:15], 0, v[32:33]
	v_lshl_add_u64 v[8:9], s[60:61], 0, v[8:9]
	v_mov_b32_e32 v14, v1
	v_mov_b32_e32 v15, v1
	s_lshl_b32 s92, s6, 2
	v_or_b32_e32 v235, 31, v59
	v_lshlrev_b32_e32 v234, 2, v58
	v_lshl_add_u64 v[202:203], v[8:9], 0, v[32:33]
	v_lshl_add_u64 v[204:205], v[4:5], 1, s[70:71]
	v_lshl_add_u64 v[214:215], v[2:3], 1, s[70:71]
	v_lshl_add_u64 v[216:217], v[0:1], 1, s[70:71]
	v_lshl_add_u64 v[218:219], v[12:13], 1, s[72:73]
	v_lshl_add_u64 v[220:221], v[10:11], 1, s[72:73]
	v_lshl_add_u64 v[222:223], v[6:7], 1, s[72:73]
	v_mov_b32_e32 v0, v1
	v_mov_b32_e32 v2, v1
	v_mov_b32_e32 v3, v1
	v_mov_b32_e32 v4, v1
	v_mov_b32_e32 v5, v1
	v_mov_b32_e32 v6, v1
	v_mov_b32_e32 v7, v1
	v_mov_b32_e32 v8, v1
	v_mov_b32_e32 v9, v1
	v_mov_b32_e32 v10, v1
	v_mov_b32_e32 v11, v1
	v_mov_b32_e32 v12, v1
	v_mov_b32_e32 v13, v1
	v_mov_b64_e32 v[46:47], v[14:15]
	v_mov_b64_e32 v[62:63], v[14:15]
	v_mov_b64_e32 v[78:79], v[14:15]
	v_mov_b64_e32 v[94:95], v[14:15]
	s_xor_b64 s[78:79], s[76:77], -1
	s_mov_b32 s7, 2
	s_add_i32 s6, s92, 4
	s_addk_i32 s68, 0x100
	s_mov_b32 s85, 0
	v_mov_b32_e32 v238, 0
	v_mov_b64_e32 v[44:45], v[12:13]
	v_mov_b64_e32 v[42:43], v[10:11]
	v_mov_b64_e32 v[40:41], v[8:9]
	v_mov_b64_e32 v[38:39], v[6:7]
	v_mov_b64_e32 v[36:37], v[4:5]
	v_mov_b64_e32 v[34:35], v[2:3]
	v_mov_b64_e32 v[32:33], v[0:1]
	v_mov_b64_e32 v[60:61], v[12:13]
	v_mov_b64_e32 v[58:59], v[10:11]
	v_mov_b64_e32 v[56:57], v[8:9]
	v_mov_b64_e32 v[54:55], v[6:7]
	v_mov_b64_e32 v[52:53], v[4:5]
	v_mov_b64_e32 v[50:51], v[2:3]
	v_mov_b64_e32 v[48:49], v[0:1]
	v_mov_b64_e32 v[76:77], v[12:13]
	v_mov_b64_e32 v[74:75], v[10:11]
	v_mov_b64_e32 v[72:73], v[8:9]
	v_mov_b64_e32 v[70:71], v[6:7]
	v_mov_b64_e32 v[68:69], v[4:5]
	v_mov_b64_e32 v[66:67], v[2:3]
	v_mov_b64_e32 v[64:65], v[0:1]
	v_mov_b64_e32 v[92:93], v[12:13]
	v_mov_b64_e32 v[90:91], v[10:11]
	v_mov_b64_e32 v[88:89], v[8:9]
	v_mov_b64_e32 v[86:87], v[6:7]
	v_mov_b64_e32 v[84:85], v[4:5]
	v_mov_b64_e32 v[82:83], v[2:3]
	v_mov_b64_e32 v[80:81], v[0:1]
	v_lshl_add_u64 v[2:3], s[8:9], 0, v[216:217]
	v_lshl_add_u64 v[4:5], s[8:9], 0, v[222:223]
	v_cndmask_b32_e32 v217, v3, v5, vcc
	v_cndmask_b32_e32 v216, v2, v4, vcc
	v_lshl_add_u64 v[2:3], s[8:9], 0, v[214:215]
	v_lshl_add_u64 v[4:5], s[8:9], 0, v[220:221]
	v_cndmask_b32_e64 v215, v3, v5, s[36:37]
	v_cndmask_b32_e64 v214, v2, v4, s[36:37]
	v_lshl_add_u64 v[2:3], s[8:9], 0, v[204:205]
	v_lshl_add_u64 v[4:5], s[8:9], 0, v[218:219]
	v_cndmask_b32_e64 v205, v3, v5, s[38:39]
	v_cndmask_b32_e64 v204, v2, v4, s[38:39]
	v_mov_b32_e32 v2, s24
	v_mov_b32_e32 v3, s25
	v_mov_b32_e32 v4, s26
	v_mov_b32_e32 v5, s27
	v_cndmask_b32_e32 v222, v2, v4, vcc
	v_cndmask_b32_e32 v223, v3, v5, vcc
	v_cndmask_b32_e64 v220, v2, v4, s[36:37]
	v_cndmask_b32_e64 v221, v3, v5, s[36:37]
	v_cndmask_b32_e64 v218, v2, v4, s[38:39]
	v_cndmask_b32_e64 v219, v3, v5, s[38:39]
	v_lshl_add_u64 v[200:201], s[8:9], 0, v[200:201]
	v_lshl_add_u64 v[202:203], s[8:9], 0, v[202:203]
	s_branch .LBB0_398
.LBB0_396:
	s_nop 8
	v_exp_f32_e32 v0, v112
	v_exp_f32_e32 v2, v113
	v_exp_f32_e32 v3, v114
	v_exp_f32_e32 v4, v115
	v_add_f32_e32 v5, 0, v0
	v_exp_f32_e32 v6, v116
	v_add_f32_e32 v5, v2, v5
	v_exp_f32_e32 v7, v117
	v_add_f32_e32 v5, v3, v5
	v_exp_f32_e32 v8, v118
	v_add_f32_e32 v5, v4, v5
	v_exp_f32_e32 v9, v119
	v_add_f32_e32 v5, v6, v5
	v_exp_f32_e32 v10, v120
	v_add_f32_e32 v5, v7, v5
	v_exp_f32_e32 v11, v121
	v_add_f32_e32 v5, v8, v5
	v_exp_f32_e32 v12, v122
	v_add_f32_e32 v5, v9, v5
	v_exp_f32_e32 v13, v123
	v_add_f32_e32 v5, v10, v5
	v_exp_f32_e32 v14, v124
	v_add_f32_e32 v5, v11, v5
	v_exp_f32_e32 v15, v125
	v_add_f32_e32 v5, v12, v5
	v_exp_f32_e32 v112, v126
	v_add_f32_e32 v5, v13, v5
	v_exp_f32_e32 v113, v127
	v_add_f32_e32 v5, v14, v5
	v_exp_f32_e32 v96, v96
	v_add_f32_e32 v5, v15, v5
	v_exp_f32_e32 v97, v97
	v_add_f32_e32 v5, v112, v5
	v_exp_f32_e32 v98, v98
	v_add_f32_e32 v5, v113, v5
	v_exp_f32_e32 v99, v99
	v_add_f32_e32 v5, v96, v5
	v_exp_f32_e32 v100, v100
	v_add_f32_e32 v5, v97, v5
	v_exp_f32_e32 v101, v101
	v_add_f32_e32 v5, v98, v5
	v_exp_f32_e32 v102, v102
	v_add_f32_e32 v5, v99, v5
	v_exp_f32_e32 v103, v103
	v_add_f32_e32 v5, v100, v5
	v_exp_f32_e32 v104, v104
	v_add_f32_e32 v5, v101, v5
	v_exp_f32_e32 v105, v105
	v_add_f32_e32 v5, v102, v5
	v_exp_f32_e32 v106, v106
	v_add_f32_e32 v5, v103, v5
	v_exp_f32_e32 v107, v107
	v_add_f32_e32 v5, v104, v5
	v_exp_f32_e32 v108, v108
	v_add_f32_e32 v5, v105, v5
	v_exp_f32_e32 v109, v109
	v_add_f32_e32 v5, v106, v5
	v_exp_f32_e32 v110, v110
	v_add_f32_e32 v5, v107, v5
	v_exp_f32_e32 v111, v111
	v_add_f32_e32 v5, v108, v5
	v_add_f32_e32 v5, v109, v5
	s_mulk_i32 s28, 0x4400
	v_add_f32_e32 v5, v110, v5
	v_add_f32_e32 v124, v111, v5
	v_cvt_pk_bf16_f32 v2, v0, v2
	v_cvt_pk_bf16_f32 v3, v3, v4
	v_cvt_pk_bf16_f32 v4, v6, v7
	v_cvt_pk_bf16_f32 v5, v8, v9
	v_cvt_pk_bf16_f32 v6, v10, v11
	v_cvt_pk_bf16_f32 v7, v12, v13
	v_cvt_pk_bf16_f32 v8, v14, v15
	v_cvt_pk_bf16_f32 v9, v112, v113
	v_cvt_pk_bf16_f32 v10, v96, v97
	v_cvt_pk_bf16_f32 v11, v98, v99
	v_cvt_pk_bf16_f32 v12, v100, v101
	v_cvt_pk_bf16_f32 v13, v102, v103
	v_cvt_pk_bf16_f32 v96, v104, v105
	v_cvt_pk_bf16_f32 v97, v106, v107
	v_cvt_pk_bf16_f32 v98, v108, v109
	v_cvt_pk_bf16_f32 v99, v110, v111
	v_add_u32_e32 v0, s28, v237
	v_add_u32_e32 v14, 0xc800, v0
	v_add_u32_e32 v15, 0xd800, v0
	v_add_u32_e32 v125, 0xe800, v0
	v_add_u32_e32 v0, 0xf800, v0
	ds_read2_b64 v[100:103], v14 offset1:2
	ds_read2_b64 v[104:107], v15 offset0:32 offset1:34
	ds_read2_b64 v[108:111], v125 offset0:64 offset1:66
	ds_read2_b64 v[112:115], v0 offset0:96 offset1:98
	ds_read2_b64 v[116:119], v14 offset0:4 offset1:6
	ds_read2_b64 v[120:123], v15 offset0:36 offset1:38
	s_waitcnt lgkmcnt(4)
	v_mfma_f32_32x32x16_bf16 v[80:95], v[100:103], v[2:5], v[80:95]
	v_mfma_f32_32x32x16_bf16 v[64:79], v[104:107], v[2:5], v[64:79]
	ds_read2_b64 v[100:103], v125 offset0:68 offset1:70
	ds_read2_b64 v[104:107], v0 offset0:100 offset1:102
	s_waitcnt lgkmcnt(4)
	v_mfma_f32_32x32x16_bf16 v[48:63], v[108:111], v[2:5], v[48:63]
	v_mfma_f32_32x32x16_bf16 v[32:47], v[112:115], v[2:5], v[32:47]
	ds_read2_b64 v[2:5], v14 offset0:8 offset1:10
	ds_read2_b64 v[108:111], v15 offset0:40 offset1:42
	s_waitcnt lgkmcnt(4)
	v_mfma_f32_32x32x16_bf16 v[80:95], v[116:119], v[6:9], v[80:95]
	v_mfma_f32_32x32x16_bf16 v[64:79], v[120:123], v[6:9], v[64:79]
	ds_read2_b64 v[112:115], v125 offset0:72 offset1:74
	ds_read2_b64 v[116:119], v0 offset0:104 offset1:106
	s_waitcnt lgkmcnt(4)
	v_mfma_f32_32x32x16_bf16 v[48:63], v[100:103], v[6:9], v[48:63]
	v_mfma_f32_32x32x16_bf16 v[32:47], v[104:107], v[6:9], v[32:47]
	ds_read2_b64 v[6:9], v14 offset0:12 offset1:14
	ds_read2_b64 v[100:103], v15 offset0:44 offset1:46
	s_waitcnt lgkmcnt(4)
	v_mfma_f32_32x32x16_bf16 v[80:95], v[2:5], v[10:13], v[80:95]
	v_mfma_f32_32x32x16_bf16 v[64:79], v[108:111], v[10:13], v[64:79]
	ds_read2_b64 v[2:5], v125 offset0:76 offset1:78
	ds_read2_b64 v[104:107], v0 offset0:108 offset1:110
	s_waitcnt lgkmcnt(4)
	v_mfma_f32_32x32x16_bf16 v[48:63], v[112:115], v[10:13], v[48:63]
	v_mfma_f32_32x32x16_bf16 v[32:47], v[116:119], v[10:13], v[32:47]
	s_waitcnt lgkmcnt(2)
	v_mfma_f32_32x32x16_bf16 v[80:95], v[6:9], v[96:99], v[80:95]
	v_mfma_f32_32x32x16_bf16 v[64:79], v[100:103], v[96:99], v[64:79]
	s_waitcnt lgkmcnt(0)
	v_mfma_f32_32x32x16_bf16 v[48:63], v[2:5], v[96:99], v[48:63]
	v_mfma_f32_32x32x16_bf16 v[32:47], v[104:107], v[96:99], v[32:47]
	v_add_f32_e32 v238, v238, v124
.LBB0_397:
	s_or_b64 exec, exec, s[76:77]
	s_add_i32 s7, s7, 1
	s_add_i32 s85, s85, 64
	v_lshl_add_u64 v[200:201], v[200:201], 0, s[20:21]
	v_lshl_add_u64 v[202:203], v[202:203], 0, s[20:21]
	v_lshl_add_u64 v[204:205], v[204:205], 0, v[218:219]
	v_lshl_add_u64 v[214:215], v[214:215], 0, v[220:221]
	v_lshl_add_u64 v[216:217], v[216:217], 0, v[222:223]
	s_cmp_lg_u32 s68, s85
	s_cbranch_scc0 .LBB0_380
.LBB0_398:
	s_add_i32 s29, s7, -2
	s_and_b32 s28, s29, 1
	s_add_i32 s0, s7, -1
	s_cmp_ge_u32 s0, s6
	s_waitcnt lgkmcnt(0)
	s_barrier
	s_mul_i32 s1, s28, 0x6400
	v_add_u32_e32 v0, s1, v236
	ds_read_b128 v[2:5], v0
	ds_read_b128 v[6:9], v0 offset:32
	ds_read_b128 v[10:13], v0 offset:12800
	ds_read_b128 v[208:211], v0 offset:12832
	ds_read_b128 v[240:243], v0 offset:64
	ds_read_b128 v[244:247], v0 offset:12864
	s_cbranch_scc1 .LBB0_401
	s_xor_b32 s0, s28, 1
	s_mul_i32 s1, s0, 0x6400
	s_add_i32 s1, s1, 0
	v_add_u32_e32 v15, s1, v225
	s_waitcnt vmcnt(0)
	ds_write_b128 v15, v[176:179]
	v_add_u32_e32 v15, s1, v224
	ds_write_b128 v15, v[180:183]
	v_add_u32_e32 v15, s1, v199
	s_mulk_i32 s0, 0x4400
	ds_write_b128 v15, v[184:187]
	v_add_u32_e32 v15, s0, v233
	v_add_u32_e32 v14, 0xc800, v15
	v_add_u32_e32 v15, 0xea00, v15
	s_cmp_ge_u32 s7, s6
	ds_write2_b64 v14, v[188:189], v[190:191] offset1:1
	ds_write2_b64 v15, v[192:193], v[194:195] offset1:1
	s_cbranch_scc1 .LBB0_401
	global_load_dwordx4 v[176:179], v[216:217], off
	global_load_dwordx4 v[180:183], v[214:215], off
	global_load_dwordx4 v[184:187], v[204:205], off
	global_load_dwordx4 v[188:191], v[200:201], off
	global_load_dwordx4 v[192:195], v[202:203], off
.LBB0_401:
	v_cmp_le_i32_e64 s[0:1], s85, v235
	s_and_saveexec_b64 s[76:77], s[0:1]
	s_cbranch_execz .LBB0_397
	s_waitcnt lgkmcnt(3)
	v_mfma_f32_32x32x16_bf16 v[112:127], v[2:5], v[128:131], v[16:31]
	v_mfma_f32_32x32x16_bf16 v[96:111], v[10:13], v[128:131], v[16:31]
	ds_read_b128 v[2:5], v0 offset:96
	ds_read_b128 v[10:13], v0 offset:12896
	s_waitcnt lgkmcnt(4)
	v_mfma_f32_32x32x16_bf16 v[112:127], v[6:9], v[132:135], v[112:127]
	v_mfma_f32_32x32x16_bf16 v[96:111], v[208:211], v[132:135], v[96:111]
	ds_read_b128 v[6:9], v0 offset:128
	ds_read_b128 v[208:211], v0 offset:12928
	s_waitcnt lgkmcnt(4)
	v_mfma_f32_32x32x16_bf16 v[112:127], v[240:243], v[136:139], v[112:127]
	v_mfma_f32_32x32x16_bf16 v[96:111], v[244:247], v[136:139], v[96:111]
	ds_read_b128 v[240:243], v0 offset:160
	ds_read_b128 v[244:247], v0 offset:12960
	s_waitcnt lgkmcnt(4)
	v_mfma_f32_32x32x16_bf16 v[112:127], v[2:5], v[140:143], v[112:127]
	v_mfma_f32_32x32x16_bf16 v[96:111], v[10:13], v[140:143], v[96:111]
	ds_read_b128 v[2:5], v0 offset:192
	ds_read_b128 v[10:13], v0 offset:12992
	s_waitcnt lgkmcnt(4)
	v_mfma_f32_32x32x16_bf16 v[112:127], v[6:9], v[144:147], v[112:127]
	v_mfma_f32_32x32x16_bf16 v[96:111], v[208:211], v[144:147], v[96:111]
	ds_read_b128 v[6:9], v0 offset:224
	ds_read_b128 v[208:211], v0 offset:13024
	s_waitcnt lgkmcnt(4)
	v_mfma_f32_32x32x16_bf16 v[112:127], v[240:243], v[148:151], v[112:127]
	v_mfma_f32_32x32x16_bf16 v[96:111], v[244:247], v[148:151], v[96:111]
	ds_read_b128 v[240:243], v0 offset:256
	ds_read_b128 v[244:247], v0 offset:13056
	s_waitcnt lgkmcnt(4)
	v_mfma_f32_32x32x16_bf16 v[112:127], v[2:5], v[152:155], v[112:127]
	v_mfma_f32_32x32x16_bf16 v[96:111], v[10:13], v[152:155], v[96:111]
	ds_read_b128 v[2:5], v0 offset:288
	ds_read_b128 v[10:13], v0 offset:13088
	s_waitcnt lgkmcnt(4)
	v_mfma_f32_32x32x16_bf16 v[112:127], v[6:9], v[156:159], v[112:127]
	v_mfma_f32_32x32x16_bf16 v[96:111], v[208:211], v[156:159], v[96:111]
	ds_read_b128 v[6:9], v0 offset:320
	ds_read_b128 v[208:211], v0 offset:13120
	s_waitcnt lgkmcnt(4)
	v_mfma_f32_32x32x16_bf16 v[112:127], v[240:243], v[160:163], v[112:127]
	v_mfma_f32_32x32x16_bf16 v[96:111], v[244:247], v[160:163], v[96:111]
	ds_read_b128 v[240:243], v0 offset:352
	ds_read_b128 v[244:247], v0 offset:13152
	s_waitcnt lgkmcnt(4)
	v_mfma_f32_32x32x16_bf16 v[112:127], v[2:5], v[168:171], v[112:127]
	v_mfma_f32_32x32x16_bf16 v[96:111], v[10:13], v[168:171], v[96:111]
	s_waitcnt lgkmcnt(2)
	v_mfma_f32_32x32x16_bf16 v[112:127], v[6:9], v[164:167], v[112:127]
	v_mfma_f32_32x32x16_bf16 v[96:111], v[208:211], v[164:167], v[96:111]
	s_waitcnt lgkmcnt(0)
	v_mfma_f32_32x32x16_bf16 v[112:127], v[240:243], v[172:175], v[112:127]
	v_mfma_f32_32x32x16_bf16 v[96:111], v[244:247], v[172:175], v[96:111]
	s_cmp_lt_u32 s29, s92
	s_cbranch_scc1 .LBB0_396
	v_add_u32_e32 v0, s85, v234
	v_cmp_gt_i32_e64 s[0:1], v0, v198
	s_nop 6
	v_cndmask_b32_e64 v2, v112, v229, s[0:1]
	v_cmp_lt_i32_e64 s[0:1], v0, v198
	s_nop 1
	v_cndmask_b32_e64 v112, v2, v112, s[0:1]
	v_add_u32_e32 v2, 2, v0
	v_cndmask_b32_e64 v113, v229, v113, s[0:1]
	v_cmp_le_i32_e64 s[0:1], v2, v198
	v_add_u32_e32 v2, 3, v0
	s_nop 0
	v_cndmask_b32_e64 v114, v229, v114, s[0:1]
	v_cmp_le_i32_e64 s[0:1], v2, v198
	v_add_u32_e32 v2, 8, v0
	s_nop 0
	v_cndmask_b32_e64 v115, v229, v115, s[0:1]
	v_cmp_le_i32_e64 s[0:1], v2, v198
	v_add_u32_e32 v2, 9, v0
	s_nop 0
	v_cndmask_b32_e64 v116, v229, v116, s[0:1]
	v_cmp_le_i32_e64 s[0:1], v2, v198
	v_add_u32_e32 v2, 10, v0
	s_nop 0
	v_cndmask_b32_e64 v117, v229, v117, s[0:1]
	v_cmp_le_i32_e64 s[0:1], v2, v198
	v_add_u32_e32 v2, 11, v0
	s_nop 0
	v_cndmask_b32_e64 v118, v229, v118, s[0:1]
	v_cmp_le_i32_e64 s[0:1], v2, v198
	v_add_u32_e32 v2, 16, v0
	s_nop 0
	v_cndmask_b32_e64 v119, v229, v119, s[0:1]
	v_cmp_le_i32_e64 s[0:1], v2, v198
	v_add_u32_e32 v2, 17, v0
	s_nop 0
	v_cndmask_b32_e64 v120, v229, v120, s[0:1]
	v_cmp_le_i32_e64 s[0:1], v2, v198
	v_add_u32_e32 v2, 18, v0
	s_nop 0
	v_cndmask_b32_e64 v121, v229, v121, s[0:1]
	v_cmp_le_i32_e64 s[0:1], v2, v198
	v_add_u32_e32 v2, 19, v0
	s_nop 0
	v_cndmask_b32_e64 v122, v229, v122, s[0:1]
	v_cmp_le_i32_e64 s[0:1], v2, v198
	v_add_u32_e32 v2, 24, v0
	s_nop 0
	v_cndmask_b32_e64 v123, v229, v123, s[0:1]
	v_cmp_le_i32_e64 s[0:1], v2, v198
	v_add_u32_e32 v2, 25, v0
	s_nop 0
	v_cndmask_b32_e64 v124, v229, v124, s[0:1]
	v_cmp_le_i32_e64 s[0:1], v2, v198
	v_add_u32_e32 v2, 26, v0
	s_nop 0
	v_cndmask_b32_e64 v125, v229, v125, s[0:1]
	v_cmp_le_i32_e64 s[0:1], v2, v198
	v_add_u32_e32 v2, 27, v0
	s_nop 0
	v_cndmask_b32_e64 v126, v229, v126, s[0:1]
	v_cmp_le_i32_e64 s[0:1], v2, v198
	v_add_u32_e32 v2, 32, v0
	s_nop 0
	v_cndmask_b32_e64 v127, v229, v127, s[0:1]
	v_cmp_le_i32_e64 s[0:1], v2, v198
	v_add_u32_e32 v2, 33, v0
	s_nop 0
	v_cndmask_b32_e64 v96, v229, v96, s[0:1]
	v_cmp_le_i32_e64 s[0:1], v2, v198
	v_add_u32_e32 v2, 34, v0
	s_nop 0
	v_cndmask_b32_e64 v97, v229, v97, s[0:1]
	v_cmp_le_i32_e64 s[0:1], v2, v198
	v_add_u32_e32 v2, 35, v0
	s_nop 0
	v_cndmask_b32_e64 v98, v229, v98, s[0:1]
	v_cmp_le_i32_e64 s[0:1], v2, v198
	v_add_u32_e32 v2, 40, v0
	s_nop 0
	v_cndmask_b32_e64 v99, v229, v99, s[0:1]
	v_cmp_le_i32_e64 s[0:1], v2, v198
	v_add_u32_e32 v2, 41, v0
	s_nop 0
	v_cndmask_b32_e64 v100, v229, v100, s[0:1]
	v_cmp_le_i32_e64 s[0:1], v2, v198
	v_add_u32_e32 v2, 42, v0
	s_nop 0
	v_cndmask_b32_e64 v101, v229, v101, s[0:1]
	v_cmp_le_i32_e64 s[0:1], v2, v198
	v_add_u32_e32 v2, 43, v0
	s_nop 0
	v_cndmask_b32_e64 v102, v229, v102, s[0:1]
	v_cmp_le_i32_e64 s[0:1], v2, v198
	v_add_u32_e32 v2, 48, v0
	s_nop 0
	v_cndmask_b32_e64 v103, v229, v103, s[0:1]
	v_cmp_le_i32_e64 s[0:1], v2, v198
	v_add_u32_e32 v2, 49, v0
	s_nop 0
	v_cndmask_b32_e64 v104, v229, v104, s[0:1]
	v_cmp_le_i32_e64 s[0:1], v2, v198
	v_add_u32_e32 v2, 50, v0
	s_nop 0
	v_cndmask_b32_e64 v105, v229, v105, s[0:1]
	v_cmp_le_i32_e64 s[0:1], v2, v198
	v_add_u32_e32 v2, 51, v0
	s_nop 0
	v_cndmask_b32_e64 v106, v229, v106, s[0:1]
	v_cmp_le_i32_e64 s[0:1], v2, v198
	v_add_u32_e32 v2, 56, v0
	s_nop 0
	v_cndmask_b32_e64 v107, v229, v107, s[0:1]
	v_cmp_le_i32_e64 s[0:1], v2, v198
	v_add_u32_e32 v2, 57, v0
	s_nop 0
	v_cndmask_b32_e64 v108, v229, v108, s[0:1]
	v_cmp_le_i32_e64 s[0:1], v2, v198
	v_add_u32_e32 v2, 58, v0
	v_add_u32_e32 v0, 59, v0
	v_cndmask_b32_e64 v109, v229, v109, s[0:1]
	v_cmp_le_i32_e64 s[0:1], v2, v198
	s_nop 1
	v_cndmask_b32_e64 v110, v229, v110, s[0:1]
	v_cmp_le_i32_e64 s[0:1], v0, v198
	s_nop 1
	v_cndmask_b32_e64 v111, v229, v111, s[0:1]
	s_branch .LBB0_396

.LBB0_737:
	s_or_b64 exec, exec, s[0:1]
	v_lshl_add_u32 v0, v217, 2, 0
	v_add_u32_e32 v136, 0x19000, v0
	s_lshl_b32 s0, s13, 1
	s_add_u32 s0, s78, s0
	s_addc_u32 s1, s79, 0
	v_or_b32_e32 v204, s14, v217
	v_mov_b32_e32 v205, s15
	v_lshlrev_b64 v[204:205], 13, v[204:205]
	v_mov_b32_e32 v208, v216
	v_ashrrev_i32_e32 v209, 31, v216
	v_lshl_add_u64 v[208:209], v[208:209], 1, s[0:1]
	v_lshlrev_b32_e32 v210, 1, v212
	v_mov_b32_e32 v211, 0
	v_lshl_add_u64 v[208:209], v[208:209], 0, v[210:211]
	v_lshl_add_u64 v[204:205], v[208:209], 0, v[204:205]
	s_mov_b32 s0, 0x20000
	s_mov_b32 s1, 0
	global_load_dwordx2 v[140:141], v[204:205], off
	global_load_dwordx2 v[142:143], v[204:205], off offset:32
	global_load_dwordx2 v[144:145], v[204:205], off offset:64
	global_load_dwordx2 v[146:147], v[204:205], off offset:96
	v_lshl_add_u64 v[204:205], v[204:205], 0, s[0:1]
	global_load_dwordx2 v[148:149], v[204:205], off
	global_load_dwordx2 v[150:151], v[204:205], off offset:32
	global_load_dwordx2 v[152:153], v[204:205], off offset:64
	global_load_dwordx2 v[154:155], v[204:205], off offset:96
	v_lshl_add_u64 v[204:205], v[204:205], 0, s[0:1]
	global_load_dwordx2 v[156:157], v[204:205], off
	global_load_dwordx2 v[158:159], v[204:205], off offset:32
	global_load_dwordx2 v[160:161], v[204:205], off offset:64
	global_load_dwordx2 v[162:163], v[204:205], off offset:96
	v_lshl_add_u64 v[204:205], v[204:205], 0, s[0:1]
	global_load_dwordx2 v[164:165], v[204:205], off
	global_load_dwordx2 v[166:167], v[204:205], off offset:32
	global_load_dwordx2 v[168:169], v[204:205], off offset:64
	global_load_dwordx2 v[170:171], v[204:205], off offset:96
	v_lshl_add_u64 v[204:205], v[204:205], 0, s[0:1]
	global_load_dwordx2 v[172:173], v[204:205], off
	global_load_dwordx2 v[174:175], v[204:205], off offset:32
	global_load_dwordx2 v[176:177], v[204:205], off offset:64
	global_load_dwordx2 v[178:179], v[204:205], off offset:96
	v_lshl_add_u64 v[204:205], v[204:205], 0, s[0:1]
	global_load_dwordx2 v[180:181], v[204:205], off
	global_load_dwordx2 v[182:183], v[204:205], off offset:32
	global_load_dwordx2 v[184:185], v[204:205], off offset:64
	global_load_dwordx2 v[186:187], v[204:205], off offset:96
	v_lshl_add_u64 v[204:205], v[204:205], 0, s[0:1]
	global_load_dwordx2 v[188:189], v[204:205], off
	global_load_dwordx2 v[190:191], v[204:205], off offset:32
	global_load_dwordx2 v[192:193], v[204:205], off offset:64
	global_load_dwordx2 v[194:195], v[204:205], off offset:96
	v_lshl_add_u64 v[204:205], v[204:205], 0, s[0:1]
	global_load_dwordx2 v[196:197], v[204:205], off
	global_load_dwordx2 v[198:199], v[204:205], off offset:32
	global_load_dwordx2 v[200:201], v[204:205], off offset:64
	global_load_dwordx2 v[202:203], v[204:205], off offset:96
	s_waitcnt lgkmcnt(0)
	s_barrier
	ds_read2st64_b32 v[134:135], v136 offset1:2
	s_lshl_b32 s0, s13, 1
	s_add_u32 s0, s78, s0
	v_or_b32_e32 v130, s14, v217
	s_addc_u32 s1, s79, 0
	v_ashrrev_i32_e32 v217, 31, v216
	v_lshl_add_u64 v[132:133], v[216:217], 1, s[0:1]
	v_lshlrev_b32_e32 v0, 1, v212
	v_lshl_add_u64 v[132:133], v[132:133], 0, v[0:1]
	s_waitcnt lgkmcnt(0)
	v_add_f32_e32 v0, 0, v134
	v_add_f32_e32 v0, v0, v135
	ds_read2st64_b32 v[134:135], v136 offset0:4 offset1:6
	s_add_i32 s12, s12, s70
	s_cmpk_lt_i32 s12, 0x400
	s_waitcnt lgkmcnt(0)
	v_add_f32_e32 v0, v0, v134
	v_add_f32_e32 v0, v0, v135
	ds_read2st64_b32 v[134:135], v136 offset0:8 offset1:10
	s_waitcnt lgkmcnt(0)
	v_add_f32_e32 v0, v0, v134
	v_add_f32_e32 v0, v0, v135
	ds_read2st64_b32 v[134:135], v136 offset0:12 offset1:14
	s_waitcnt lgkmcnt(0)
	v_add_f32_e32 v0, v0, v134
	v_add_f32_e32 v0, v0, v135
	v_fmamk_f32 v0, v0, 0x3b000000, v207
	v_cmp_gt_f32_e32 vcc, s87, v0
	v_mul_f32_e32 v131, 0x4b800000, v0
	s_nop 0
	v_cndmask_b32_e32 v0, v0, v131, vcc
	v_rsq_f32_e32 v0, v0
	s_nop 0
	v_mul_f32_e32 v131, 0x45800000, v0
	v_cndmask_b32_e32 v0, v0, v131, vcc
	v_mov_b32_e32 v131, s15
	v_lshlrev_b64 v[134:135], 13, v[130:131]
	v_lshl_add_u64 v[134:135], v[132:133], 0, v[134:135]
	s_waitcnt vmcnt(31)
	v_mov_b32_e32 v138, v140
	v_mov_b32_e32 v139, v141
	v_lshlrev_b32_e32 v137, 16, v138
	v_mul_f32_e32 v126, v126, v137
	v_and_b32_e32 v137, 0xffff0000, v138
	v_mul_f32_e32 v127, v127, v137
	v_mul_f32_e32 v126, v126, v0
	v_mul_f32_e32 v127, v127, v0
	v_cvt_pk_bf16_f32 v126, v126, v127
	v_lshlrev_b32_e32 v127, 16, v139
	v_mul_f32_e32 v127, v128, v127
	v_and_b32_e32 v128, 0xffff0000, v139
	v_mul_f32_e32 v127, v127, v0
	v_mul_f32_e32 v128, v129, v128
	v_mul_f32_e32 v128, v128, v0
	v_cvt_pk_bf16_f32 v127, v127, v128
	global_store_dwordx2 v[134:135], v[126:127], off
	s_waitcnt vmcnt(31)
	v_mov_b32_e32 v126, v142
	v_mov_b32_e32 v127, v143
	v_lshlrev_b32_e32 v128, 16, v126
	v_and_b32_e32 v126, 0xffff0000, v126
	v_mul_f32_e32 v122, v122, v128
	v_mul_f32_e32 v123, v123, v126
	v_mul_f32_e32 v122, v0, v122
	v_mul_f32_e32 v123, v0, v123
	v_cvt_pk_bf16_f32 v122, v122, v123
	v_lshlrev_b32_e32 v123, 16, v127
	v_mul_f32_e32 v123, v124, v123
	v_and_b32_e32 v124, 0xffff0000, v127
	v_mul_f32_e32 v123, v0, v123
	v_mul_f32_e32 v124, v125, v124
	v_mul_f32_e32 v124, v0, v124
	v_cvt_pk_bf16_f32 v123, v123, v124
	global_store_dwordx2 v[134:135], v[122:123], off offset:32
	s_waitcnt vmcnt(31)
	v_mov_b32_e32 v122, v144
	v_mov_b32_e32 v123, v145
	v_lshlrev_b32_e32 v124, 16, v122
	v_and_b32_e32 v122, 0xffff0000, v122
	v_mul_f32_e32 v118, v118, v124
	v_mul_f32_e32 v119, v119, v122
	v_mul_f32_e32 v118, v0, v118
	v_mul_f32_e32 v119, v0, v119
	v_cvt_pk_bf16_f32 v118, v118, v119
	v_lshlrev_b32_e32 v119, 16, v123
	v_mul_f32_e32 v119, v120, v119
	v_and_b32_e32 v120, 0xffff0000, v123
	v_mul_f32_e32 v119, v0, v119
	v_mul_f32_e32 v120, v121, v120
	v_mul_f32_e32 v120, v0, v120
	v_cvt_pk_bf16_f32 v119, v119, v120
	global_store_dwordx2 v[134:135], v[118:119], off offset:64
	s_waitcnt vmcnt(31)
	v_mov_b32_e32 v118, v146
	v_mov_b32_e32 v119, v147
	v_lshlrev_b32_e32 v120, 16, v118
	v_and_b32_e32 v118, 0xffff0000, v118
	v_mul_f32_e32 v114, v114, v120
	v_mul_f32_e32 v115, v115, v118
	v_mul_f32_e32 v114, v0, v114
	v_mul_f32_e32 v115, v0, v115
	v_cvt_pk_bf16_f32 v114, v114, v115
	v_lshlrev_b32_e32 v115, 16, v119
	v_mul_f32_e32 v115, v116, v115
	v_and_b32_e32 v116, 0xffff0000, v119
	v_mul_f32_e32 v115, v0, v115
	v_mul_f32_e32 v116, v117, v116
	v_mul_f32_e32 v0, v0, v116
	v_cvt_pk_bf16_f32 v115, v115, v0
	global_store_dwordx2 v[134:135], v[114:115], off offset:96
	ds_read2_b32 v[114:115], v136 offset0:16 offset1:144
	s_waitcnt lgkmcnt(0)
	v_add_f32_e32 v0, 0, v114
	v_add_f32_e32 v116, v0, v115
	v_add_u32_e32 v0, 64, v136
	ds_read2st64_b32 v[114:115], v0 offset0:4 offset1:6
	s_waitcnt lgkmcnt(0)
	v_add_f32_e32 v114, v116, v114
	v_add_f32_e32 v116, v114, v115
	ds_read2st64_b32 v[114:115], v0 offset0:8 offset1:10
	s_waitcnt lgkmcnt(0)
	v_add_f32_e32 v114, v116, v114
	v_add_f32_e32 v116, v114, v115
	ds_read2st64_b32 v[114:115], v0 offset0:12 offset1:14
	s_waitcnt lgkmcnt(0)
	v_add_f32_e32 v114, v116, v114
	v_add_f32_e32 v114, v114, v115
	v_fmamk_f32 v114, v114, 0x3b000000, v207
	v_cmp_gt_f32_e32 vcc, s87, v114
	v_mul_f32_e32 v115, 0x4b800000, v114
	s_nop 0
	v_cndmask_b32_e32 v114, v114, v115, vcc
	v_rsq_f32_e32 v114, v114
	s_nop 0
	v_mul_f32_e32 v115, 0x45800000, v114
	v_cndmask_b32_e32 v116, v114, v115, vcc
	v_or_b32_e32 v114, 16, v130
	v_mov_b32_e32 v115, s15
	v_lshlrev_b64 v[114:115], 13, v[114:115]
	v_lshl_add_u64 v[114:115], v[132:133], 0, v[114:115]
	s_waitcnt vmcnt(31)
	v_mov_b32_e32 v118, v148
	v_mov_b32_e32 v119, v149
	v_lshlrev_b32_e32 v117, 16, v118
	v_mul_f32_e32 v110, v110, v117
	v_and_b32_e32 v117, 0xffff0000, v118
	v_mul_f32_e32 v111, v111, v117
	v_mul_f32_e32 v110, v110, v116
	v_mul_f32_e32 v111, v111, v116
	v_cvt_pk_bf16_f32 v110, v110, v111
	v_lshlrev_b32_e32 v111, 16, v119
	v_mul_f32_e32 v111, v112, v111
	v_and_b32_e32 v112, 0xffff0000, v119
	v_mul_f32_e32 v111, v111, v116
	v_mul_f32_e32 v112, v113, v112
	v_mul_f32_e32 v112, v112, v116
	v_cvt_pk_bf16_f32 v111, v111, v112
	global_store_dwordx2 v[114:115], v[110:111], off
	s_waitcnt vmcnt(31)
	v_mov_b32_e32 v110, v150
	v_mov_b32_e32 v111, v151
	v_lshlrev_b32_e32 v112, 16, v110
	v_and_b32_e32 v110, 0xffff0000, v110
	v_mul_f32_e32 v106, v106, v112
	v_mul_f32_e32 v107, v107, v110
	v_mul_f32_e32 v106, v116, v106
	v_mul_f32_e32 v107, v116, v107
	v_cvt_pk_bf16_f32 v106, v106, v107
	v_lshlrev_b32_e32 v107, 16, v111
	v_mul_f32_e32 v107, v108, v107
	v_and_b32_e32 v108, 0xffff0000, v111
	v_mul_f32_e32 v107, v116, v107
	v_mul_f32_e32 v108, v109, v108
	v_mul_f32_e32 v108, v116, v108
	v_cvt_pk_bf16_f32 v107, v107, v108
	global_store_dwordx2 v[114:115], v[106:107], off offset:32
	s_waitcnt vmcnt(31)
	v_mov_b32_e32 v106, v152
	v_mov_b32_e32 v107, v153
	v_lshlrev_b32_e32 v108, 16, v106
	v_and_b32_e32 v106, 0xffff0000, v106
	v_mul_f32_e32 v102, v102, v108
	v_mul_f32_e32 v103, v103, v106
	v_mul_f32_e32 v102, v116, v102
	v_mul_f32_e32 v103, v116, v103
	v_cvt_pk_bf16_f32 v102, v102, v103
	v_lshlrev_b32_e32 v103, 16, v107
	v_mul_f32_e32 v103, v104, v103
	v_and_b32_e32 v104, 0xffff0000, v107
	v_mul_f32_e32 v103, v116, v103
	v_mul_f32_e32 v104, v105, v104
	v_mul_f32_e32 v104, v116, v104
	v_cvt_pk_bf16_f32 v103, v103, v104
	global_store_dwordx2 v[114:115], v[102:103], off offset:64
	s_waitcnt vmcnt(31)
	v_mov_b32_e32 v102, v154
	v_mov_b32_e32 v103, v155
	v_lshlrev_b32_e32 v104, 16, v102
	v_and_b32_e32 v102, 0xffff0000, v102
	v_mul_f32_e32 v98, v98, v104
	v_mul_f32_e32 v99, v99, v102
	v_mul_f32_e32 v98, v116, v98
	v_mul_f32_e32 v99, v116, v99
	v_cvt_pk_bf16_f32 v98, v98, v99
	v_lshlrev_b32_e32 v99, 16, v103
	v_mul_f32_e32 v99, v100, v99
	v_and_b32_e32 v100, 0xffff0000, v103
	v_mul_f32_e32 v99, v116, v99
	v_mul_f32_e32 v100, v101, v100
	v_mul_f32_e32 v100, v116, v100
	v_cvt_pk_bf16_f32 v99, v99, v100
	global_store_dwordx2 v[114:115], v[98:99], off offset:96
	ds_read2_b32 v[98:99], v136 offset0:32 offset1:160
	v_add_u32_e32 v100, 0x80, v136
	s_waitcnt lgkmcnt(0)
	v_add_f32_e32 v98, 0, v98
	v_add_f32_e32 v101, v98, v99
	ds_read2st64_b32 v[98:99], v100 offset0:4 offset1:6
	s_waitcnt lgkmcnt(0)
	v_add_f32_e32 v98, v101, v98
	v_add_f32_e32 v101, v98, v99
	ds_read2st64_b32 v[98:99], v100 offset0:8 offset1:10
	s_waitcnt lgkmcnt(0)
	v_add_f32_e32 v98, v101, v98
	v_add_f32_e32 v101, v98, v99
	ds_read2st64_b32 v[98:99], v100 offset0:12 offset1:14
	s_waitcnt lgkmcnt(0)
	v_add_f32_e32 v98, v101, v98
	v_add_f32_e32 v98, v98, v99
	v_fmamk_f32 v98, v98, 0x3b000000, v207
	v_cmp_gt_f32_e32 vcc, s87, v98
	v_mul_f32_e32 v99, 0x4b800000, v98
	s_nop 0
	v_cndmask_b32_e32 v98, v98, v99, vcc
	v_rsq_f32_e32 v98, v98
	s_nop 0
	v_mul_f32_e32 v99, 0x45800000, v98
	v_cndmask_b32_e32 v101, v98, v99, vcc
	v_or_b32_e32 v98, 32, v130
	v_mov_b32_e32 v99, s15
	v_lshlrev_b64 v[98:99], 13, v[98:99]
	v_lshl_add_u64 v[98:99], v[132:133], 0, v[98:99]
	s_waitcnt vmcnt(31)
	v_mov_b32_e32 v102, v156
	v_mov_b32_e32 v103, v157
	v_lshlrev_b32_e32 v104, 16, v102
	v_and_b32_e32 v102, 0xffff0000, v102
	v_mul_f32_e32 v94, v94, v104
	v_mul_f32_e32 v95, v95, v102
	v_mul_f32_e32 v94, v94, v101
	v_mul_f32_e32 v95, v95, v101
	v_cvt_pk_bf16_f32 v94, v94, v95
	v_lshlrev_b32_e32 v95, 16, v103
	v_mul_f32_e32 v95, v96, v95
	v_and_b32_e32 v96, 0xffff0000, v103
	v_mul_f32_e32 v95, v95, v101
	v_mul_f32_e32 v96, v97, v96
	v_mul_f32_e32 v96, v96, v101
	v_cvt_pk_bf16_f32 v95, v95, v96
	global_store_dwordx2 v[98:99], v[94:95], off
	s_waitcnt vmcnt(31)
	v_mov_b32_e32 v94, v158
	v_mov_b32_e32 v95, v159
	v_lshlrev_b32_e32 v96, 16, v94
	v_and_b32_e32 v94, 0xffff0000, v94
	v_mul_f32_e32 v90, v90, v96
	v_mul_f32_e32 v91, v91, v94
	v_mul_f32_e32 v90, v101, v90
	v_mul_f32_e32 v91, v101, v91
	v_cvt_pk_bf16_f32 v90, v90, v91
	v_lshlrev_b32_e32 v91, 16, v95
	v_mul_f32_e32 v91, v92, v91
	v_and_b32_e32 v92, 0xffff0000, v95
	v_mul_f32_e32 v91, v101, v91
	v_mul_f32_e32 v92, v93, v92
	v_mul_f32_e32 v92, v101, v92
	v_cvt_pk_bf16_f32 v91, v91, v92
	global_store_dwordx2 v[98:99], v[90:91], off offset:32
	s_waitcnt vmcnt(31)
	v_mov_b32_e32 v90, v160
	v_mov_b32_e32 v91, v161
	v_lshlrev_b32_e32 v92, 16, v90
	v_and_b32_e32 v90, 0xffff0000, v90
	v_mul_f32_e32 v86, v86, v92
	v_mul_f32_e32 v87, v87, v90
	v_mul_f32_e32 v86, v101, v86
	v_mul_f32_e32 v87, v101, v87
	v_cvt_pk_bf16_f32 v86, v86, v87
	v_lshlrev_b32_e32 v87, 16, v91
	v_mul_f32_e32 v87, v88, v87
	v_and_b32_e32 v88, 0xffff0000, v91
	v_mul_f32_e32 v87, v101, v87
	v_mul_f32_e32 v88, v89, v88
	v_mul_f32_e32 v88, v101, v88
	v_cvt_pk_bf16_f32 v87, v87, v88
	global_store_dwordx2 v[98:99], v[86:87], off offset:64
	s_waitcnt vmcnt(31)
	v_mov_b32_e32 v86, v162
	v_mov_b32_e32 v87, v163
	v_lshlrev_b32_e32 v88, 16, v86
	v_and_b32_e32 v86, 0xffff0000, v86
	v_mul_f32_e32 v82, v82, v88
	v_mul_f32_e32 v83, v83, v86
	v_mul_f32_e32 v82, v101, v82
	v_mul_f32_e32 v83, v101, v83
	v_cvt_pk_bf16_f32 v82, v82, v83
	v_lshlrev_b32_e32 v83, 16, v87
	v_mul_f32_e32 v83, v84, v83
	v_and_b32_e32 v84, 0xffff0000, v87
	v_mul_f32_e32 v83, v101, v83
	v_mul_f32_e32 v84, v85, v84
	v_mul_f32_e32 v84, v101, v84
	v_cvt_pk_bf16_f32 v83, v83, v84
	global_store_dwordx2 v[98:99], v[82:83], off offset:96
	ds_read2_b32 v[82:83], v136 offset0:48 offset1:176
	v_add_u32_e32 v84, 0xc0, v136
	s_waitcnt lgkmcnt(0)
	v_add_f32_e32 v82, 0, v82
	v_add_f32_e32 v85, v82, v83
	ds_read2st64_b32 v[82:83], v84 offset0:4 offset1:6
	s_waitcnt lgkmcnt(0)
	v_add_f32_e32 v82, v85, v82
	v_add_f32_e32 v85, v82, v83
	ds_read2st64_b32 v[82:83], v84 offset0:8 offset1:10
	s_waitcnt lgkmcnt(0)
	v_add_f32_e32 v82, v85, v82
	v_add_f32_e32 v85, v82, v83
	ds_read2st64_b32 v[82:83], v84 offset0:12 offset1:14
	s_waitcnt lgkmcnt(0)
	v_add_f32_e32 v82, v85, v82
	v_add_f32_e32 v82, v82, v83
	v_fmamk_f32 v82, v82, 0x3b000000, v207
	v_cmp_gt_f32_e32 vcc, s87, v82
	v_mul_f32_e32 v83, 0x4b800000, v82
	s_nop 0
	v_cndmask_b32_e32 v82, v82, v83, vcc
	v_rsq_f32_e32 v82, v82
	s_nop 0
	v_mul_f32_e32 v83, 0x45800000, v82
	v_cndmask_b32_e32 v85, v82, v83, vcc
	v_or_b32_e32 v82, 48, v130
	v_mov_b32_e32 v83, s15
	v_lshlrev_b64 v[82:83], 13, v[82:83]
	v_lshl_add_u64 v[82:83], v[132:133], 0, v[82:83]
	s_waitcnt vmcnt(31)
	v_mov_b32_e32 v86, v164
	v_mov_b32_e32 v87, v165
	v_lshlrev_b32_e32 v88, 16, v86
	v_and_b32_e32 v86, 0xffff0000, v86
	v_mul_f32_e32 v78, v78, v88
	v_mul_f32_e32 v79, v79, v86
	v_mul_f32_e32 v78, v78, v85
	v_mul_f32_e32 v79, v79, v85
	v_cvt_pk_bf16_f32 v78, v78, v79
	v_lshlrev_b32_e32 v79, 16, v87
	v_mul_f32_e32 v79, v80, v79
	v_and_b32_e32 v80, 0xffff0000, v87
	v_mul_f32_e32 v79, v79, v85
	v_mul_f32_e32 v80, v81, v80
	v_mul_f32_e32 v80, v80, v85
	v_cvt_pk_bf16_f32 v79, v79, v80
	global_store_dwordx2 v[82:83], v[78:79], off
	s_waitcnt vmcnt(31)
	v_mov_b32_e32 v78, v166
	v_mov_b32_e32 v79, v167
	v_lshlrev_b32_e32 v80, 16, v78
	v_and_b32_e32 v78, 0xffff0000, v78
	v_mul_f32_e32 v74, v74, v80
	v_mul_f32_e32 v75, v75, v78
	v_mul_f32_e32 v74, v85, v74
	v_mul_f32_e32 v75, v85, v75
	v_cvt_pk_bf16_f32 v74, v74, v75
	v_lshlrev_b32_e32 v75, 16, v79
	v_mul_f32_e32 v75, v76, v75
	v_and_b32_e32 v76, 0xffff0000, v79
	v_mul_f32_e32 v75, v85, v75
	v_mul_f32_e32 v76, v77, v76
	v_mul_f32_e32 v76, v85, v76
	v_cvt_pk_bf16_f32 v75, v75, v76
	global_store_dwordx2 v[82:83], v[74:75], off offset:32
	s_waitcnt vmcnt(31)
	v_mov_b32_e32 v74, v168
	v_mov_b32_e32 v75, v169
	v_lshlrev_b32_e32 v76, 16, v74
	v_and_b32_e32 v74, 0xffff0000, v74
	v_mul_f32_e32 v70, v70, v76
	v_mul_f32_e32 v71, v71, v74
	v_mul_f32_e32 v70, v85, v70
	v_mul_f32_e32 v71, v85, v71
	v_cvt_pk_bf16_f32 v70, v70, v71
	v_lshlrev_b32_e32 v71, 16, v75
	v_mul_f32_e32 v71, v72, v71
	v_and_b32_e32 v72, 0xffff0000, v75
	v_mul_f32_e32 v71, v85, v71
	v_mul_f32_e32 v72, v73, v72
	v_mul_f32_e32 v72, v85, v72
	v_cvt_pk_bf16_f32 v71, v71, v72
	global_store_dwordx2 v[82:83], v[70:71], off offset:64
	s_waitcnt vmcnt(31)
	v_mov_b32_e32 v70, v170
	v_mov_b32_e32 v71, v171
	v_lshlrev_b32_e32 v72, 16, v70
	v_and_b32_e32 v70, 0xffff0000, v70
	v_mul_f32_e32 v66, v66, v72
	v_mul_f32_e32 v67, v67, v70
	v_mul_f32_e32 v66, v85, v66
	v_mul_f32_e32 v67, v85, v67
	v_cvt_pk_bf16_f32 v66, v66, v67
	v_lshlrev_b32_e32 v67, 16, v71
	v_mul_f32_e32 v67, v68, v67
	v_and_b32_e32 v68, 0xffff0000, v71
	v_mul_f32_e32 v67, v85, v67
	v_mul_f32_e32 v68, v69, v68
	v_mul_f32_e32 v68, v85, v68
	v_cvt_pk_bf16_f32 v67, v67, v68
	global_store_dwordx2 v[82:83], v[66:67], off offset:96
	ds_read2st64_b32 v[66:67], v136 offset0:1 offset1:3
	s_waitcnt lgkmcnt(0)
	v_add_f32_e32 v66, 0, v66
	v_add_f32_e32 v68, v66, v67
	ds_read2st64_b32 v[66:67], v136 offset0:5 offset1:7
	s_waitcnt lgkmcnt(0)
	v_add_f32_e32 v66, v68, v66
	v_add_f32_e32 v68, v66, v67
	ds_read2st64_b32 v[66:67], v136 offset0:9 offset1:11
	s_waitcnt lgkmcnt(0)
	v_add_f32_e32 v66, v68, v66
	v_add_f32_e32 v68, v66, v67
	ds_read2st64_b32 v[66:67], v136 offset0:13 offset1:15
	s_waitcnt lgkmcnt(0)
	v_add_f32_e32 v66, v68, v66
	v_add_f32_e32 v66, v66, v67
	v_fmamk_f32 v66, v66, 0x3b000000, v207
	v_cmp_gt_f32_e32 vcc, s87, v66
	v_mul_f32_e32 v67, 0x4b800000, v66
	s_nop 0
	v_cndmask_b32_e32 v66, v66, v67, vcc
	v_rsq_f32_e32 v66, v66
	s_nop 0
	v_mul_f32_e32 v67, 0x45800000, v66
	v_cndmask_b32_e32 v68, v66, v67, vcc
	v_or_b32_e32 v66, 64, v130
	v_mov_b32_e32 v67, s15
	v_lshlrev_b64 v[66:67], 13, v[66:67]
	v_lshl_add_u64 v[66:67], v[132:133], 0, v[66:67]
	s_waitcnt vmcnt(31)
	v_mov_b32_e32 v70, v172
	v_mov_b32_e32 v71, v173
	v_lshlrev_b32_e32 v69, 16, v70
	v_mul_f32_e32 v62, v62, v69
	v_and_b32_e32 v69, 0xffff0000, v70
	v_mul_f32_e32 v63, v63, v69
	v_mul_f32_e32 v62, v62, v68
	v_mul_f32_e32 v63, v63, v68
	v_cvt_pk_bf16_f32 v62, v62, v63
	v_lshlrev_b32_e32 v63, 16, v71
	v_mul_f32_e32 v63, v64, v63
	v_and_b32_e32 v64, 0xffff0000, v71
	v_mul_f32_e32 v63, v63, v68
	v_mul_f32_e32 v64, v65, v64
	v_mul_f32_e32 v64, v64, v68
	v_cvt_pk_bf16_f32 v63, v63, v64
	global_store_dwordx2 v[66:67], v[62:63], off
	s_waitcnt vmcnt(31)
	v_mov_b32_e32 v62, v174
	v_mov_b32_e32 v63, v175
	v_lshlrev_b32_e32 v64, 16, v62
	v_and_b32_e32 v62, 0xffff0000, v62
	v_mul_f32_e32 v58, v58, v64
	v_mul_f32_e32 v59, v59, v62
	v_mul_f32_e32 v58, v68, v58
	v_mul_f32_e32 v59, v68, v59
	v_cvt_pk_bf16_f32 v58, v58, v59
	v_lshlrev_b32_e32 v59, 16, v63
	v_mul_f32_e32 v59, v60, v59
	v_and_b32_e32 v60, 0xffff0000, v63
	v_mul_f32_e32 v59, v68, v59
	v_mul_f32_e32 v60, v61, v60
	v_mul_f32_e32 v60, v68, v60
	v_cvt_pk_bf16_f32 v59, v59, v60
	global_store_dwordx2 v[66:67], v[58:59], off offset:32
	s_waitcnt vmcnt(31)
	v_mov_b32_e32 v58, v176
	v_mov_b32_e32 v59, v177
	v_lshlrev_b32_e32 v60, 16, v58
	v_and_b32_e32 v58, 0xffff0000, v58
	v_mul_f32_e32 v54, v54, v60
	v_mul_f32_e32 v55, v55, v58
	v_mul_f32_e32 v54, v68, v54
	v_mul_f32_e32 v55, v68, v55
	v_cvt_pk_bf16_f32 v54, v54, v55
	v_lshlrev_b32_e32 v55, 16, v59
	v_mul_f32_e32 v55, v56, v55
	v_and_b32_e32 v56, 0xffff0000, v59
	v_mul_f32_e32 v55, v68, v55
	v_mul_f32_e32 v56, v57, v56
	v_mul_f32_e32 v56, v68, v56
	v_cvt_pk_bf16_f32 v55, v55, v56
	global_store_dwordx2 v[66:67], v[54:55], off offset:64
	s_waitcnt vmcnt(31)
	v_mov_b32_e32 v54, v178
	v_mov_b32_e32 v55, v179
	v_lshlrev_b32_e32 v56, 16, v54
	v_and_b32_e32 v54, 0xffff0000, v54
	v_mul_f32_e32 v50, v50, v56
	v_mul_f32_e32 v51, v51, v54
	v_mul_f32_e32 v50, v68, v50
	v_mul_f32_e32 v51, v68, v51
	v_cvt_pk_bf16_f32 v50, v50, v51
	v_lshlrev_b32_e32 v51, 16, v55
	v_mul_f32_e32 v51, v52, v51
	v_and_b32_e32 v52, 0xffff0000, v55
	v_mul_f32_e32 v51, v68, v51
	v_mul_f32_e32 v52, v53, v52
	v_mul_f32_e32 v52, v68, v52
	v_cvt_pk_bf16_f32 v51, v51, v52
	global_store_dwordx2 v[66:67], v[50:51], off offset:96
	ds_read2_b32 v[50:51], v136 offset0:80 offset1:208
	s_waitcnt lgkmcnt(0)
	v_add_f32_e32 v50, 0, v50
	v_add_f32_e32 v52, v50, v51
	ds_read2st64_b32 v[50:51], v0 offset0:5 offset1:7
	s_waitcnt lgkmcnt(0)
	v_add_f32_e32 v50, v52, v50
	v_add_f32_e32 v52, v50, v51
	ds_read2st64_b32 v[50:51], v0 offset0:9 offset1:11
	s_waitcnt lgkmcnt(0)
	v_add_f32_e32 v50, v52, v50
	v_add_f32_e32 v52, v50, v51
	ds_read2st64_b32 v[50:51], v0 offset0:13 offset1:15
	s_waitcnt lgkmcnt(0)
	v_add_f32_e32 v0, v52, v50
	v_add_f32_e32 v0, v0, v51
	v_fmamk_f32 v0, v0, 0x3b000000, v207
	v_cmp_gt_f32_e32 vcc, s87, v0
	v_mul_f32_e32 v50, 0x4b800000, v0
	v_mov_b32_e32 v51, s15
	v_cndmask_b32_e32 v0, v0, v50, vcc
	v_rsq_f32_e32 v0, v0
	s_nop 0
	v_mul_f32_e32 v50, 0x45800000, v0
	v_cndmask_b32_e32 v0, v0, v50, vcc
	v_or_b32_e32 v50, 0x50, v130
	v_lshlrev_b64 v[50:51], 13, v[50:51]
	v_lshl_add_u64 v[50:51], v[132:133], 0, v[50:51]
	s_waitcnt vmcnt(31)
	v_mov_b32_e32 v52, v180
	v_mov_b32_e32 v53, v181
	v_lshlrev_b32_e32 v54, 16, v52
	v_and_b32_e32 v52, 0xffff0000, v52
	v_mul_f32_e32 v46, v46, v54
	v_mul_f32_e32 v47, v47, v52
	v_mul_f32_e32 v46, v46, v0
	v_mul_f32_e32 v47, v47, v0
	v_cvt_pk_bf16_f32 v46, v46, v47
	v_lshlrev_b32_e32 v47, 16, v53
	v_mul_f32_e32 v47, v48, v47
	v_and_b32_e32 v48, 0xffff0000, v53
	v_mul_f32_e32 v47, v47, v0
	v_mul_f32_e32 v48, v49, v48
	v_mul_f32_e32 v48, v48, v0
	v_cvt_pk_bf16_f32 v47, v47, v48
	global_store_dwordx2 v[50:51], v[46:47], off
	s_waitcnt vmcnt(31)
	v_mov_b32_e32 v46, v182
	v_mov_b32_e32 v47, v183
	v_lshlrev_b32_e32 v48, 16, v46
	v_and_b32_e32 v46, 0xffff0000, v46
	v_mul_f32_e32 v42, v42, v48
	v_mul_f32_e32 v43, v43, v46
	v_mul_f32_e32 v42, v0, v42
	v_mul_f32_e32 v43, v0, v43
	v_cvt_pk_bf16_f32 v42, v42, v43
	v_lshlrev_b32_e32 v43, 16, v47
	v_mul_f32_e32 v43, v44, v43
	v_and_b32_e32 v44, 0xffff0000, v47
	v_mul_f32_e32 v43, v0, v43
	v_mul_f32_e32 v44, v45, v44
	v_mul_f32_e32 v44, v0, v44
	v_cvt_pk_bf16_f32 v43, v43, v44
	global_store_dwordx2 v[50:51], v[42:43], off offset:32
	s_waitcnt vmcnt(31)
	v_mov_b32_e32 v42, v184
	v_mov_b32_e32 v43, v185
	v_lshlrev_b32_e32 v44, 16, v42
	v_and_b32_e32 v42, 0xffff0000, v42
	v_mul_f32_e32 v38, v38, v44
	v_mul_f32_e32 v39, v39, v42
	v_mul_f32_e32 v38, v0, v38
	v_mul_f32_e32 v39, v0, v39
	v_cvt_pk_bf16_f32 v38, v38, v39
	v_lshlrev_b32_e32 v39, 16, v43
	v_mul_f32_e32 v39, v40, v39
	v_and_b32_e32 v40, 0xffff0000, v43
	v_mul_f32_e32 v39, v0, v39
	v_mul_f32_e32 v40, v41, v40
	v_mul_f32_e32 v40, v0, v40
	v_cvt_pk_bf16_f32 v39, v39, v40
	global_store_dwordx2 v[50:51], v[38:39], off offset:64
	s_waitcnt vmcnt(31)
	v_mov_b32_e32 v38, v186
	v_mov_b32_e32 v39, v187
	v_lshlrev_b32_e32 v40, 16, v38
	v_and_b32_e32 v38, 0xffff0000, v38
	v_mul_f32_e32 v34, v34, v40
	v_mul_f32_e32 v35, v35, v38
	v_mul_f32_e32 v34, v0, v34
	v_mul_f32_e32 v35, v0, v35
	v_cvt_pk_bf16_f32 v34, v34, v35
	v_lshlrev_b32_e32 v35, 16, v39
	v_mul_f32_e32 v35, v36, v35
	v_and_b32_e32 v36, 0xffff0000, v39
	v_mul_f32_e32 v35, v0, v35
	v_mul_f32_e32 v36, v37, v36
	v_mul_f32_e32 v0, v0, v36
	v_cvt_pk_bf16_f32 v35, v35, v0
	global_store_dwordx2 v[50:51], v[34:35], off offset:96
	ds_read2_b32 v[34:35], v136 offset0:96 offset1:224
	s_waitcnt lgkmcnt(0)
	v_add_f32_e32 v0, 0, v34
	v_add_f32_e32 v0, v0, v35
	ds_read2st64_b32 v[34:35], v100 offset0:5 offset1:7
	s_waitcnt lgkmcnt(0)
	v_add_f32_e32 v0, v0, v34
	v_add_f32_e32 v0, v0, v35
	ds_read2st64_b32 v[34:35], v100 offset0:9 offset1:11
	s_waitcnt lgkmcnt(0)
	v_add_f32_e32 v0, v0, v34
	v_add_f32_e32 v0, v0, v35
	ds_read2st64_b32 v[34:35], v100 offset0:13 offset1:15
	s_waitcnt lgkmcnt(0)
	v_add_f32_e32 v0, v0, v34
	v_add_f32_e32 v0, v0, v35
	v_fmamk_f32 v0, v0, 0x3b000000, v207
	v_cmp_gt_f32_e32 vcc, s87, v0
	v_mul_f32_e32 v34, 0x4b800000, v0
	v_mov_b32_e32 v35, s15
	v_cndmask_b32_e32 v0, v0, v34, vcc
	v_rsq_f32_e32 v0, v0
	s_nop 0
	v_mul_f32_e32 v34, 0x45800000, v0
	v_cndmask_b32_e32 v0, v0, v34, vcc
	v_or_b32_e32 v34, 0x60, v130
	v_lshlrev_b64 v[34:35], 13, v[34:35]
	v_lshl_add_u64 v[34:35], v[132:133], 0, v[34:35]
	v_or_b32_e32 v130, 0x70, v130
	s_waitcnt vmcnt(31)
	v_mov_b32_e32 v36, v188
	v_mov_b32_e32 v37, v189
	v_lshlrev_b32_e32 v38, 16, v36
	v_and_b32_e32 v36, 0xffff0000, v36
	v_mul_f32_e32 v30, v30, v38
	v_mul_f32_e32 v31, v31, v36
	v_mul_f32_e32 v30, v30, v0
	v_mul_f32_e32 v31, v31, v0
	v_cvt_pk_bf16_f32 v30, v30, v31
	v_lshlrev_b32_e32 v31, 16, v37
	v_mul_f32_e32 v31, v32, v31
	v_and_b32_e32 v32, 0xffff0000, v37
	v_mul_f32_e32 v31, v31, v0
	v_mul_f32_e32 v32, v33, v32
	v_mul_f32_e32 v32, v32, v0
	v_cvt_pk_bf16_f32 v31, v31, v32
	global_store_dwordx2 v[34:35], v[30:31], off
	s_waitcnt vmcnt(31)
	v_mov_b32_e32 v30, v190
	v_mov_b32_e32 v31, v191
	v_lshlrev_b32_e32 v32, 16, v30
	v_and_b32_e32 v30, 0xffff0000, v30
	v_mul_f32_e32 v26, v26, v32
	v_mul_f32_e32 v27, v27, v30
	v_mul_f32_e32 v26, v0, v26
	v_mul_f32_e32 v27, v0, v27
	v_cvt_pk_bf16_f32 v26, v26, v27
	v_lshlrev_b32_e32 v27, 16, v31
	v_mul_f32_e32 v27, v28, v27
	v_and_b32_e32 v28, 0xffff0000, v31
	v_mul_f32_e32 v27, v0, v27
	v_mul_f32_e32 v28, v29, v28
	v_mul_f32_e32 v28, v0, v28
	v_cvt_pk_bf16_f32 v27, v27, v28
	global_store_dwordx2 v[34:35], v[26:27], off offset:32
	s_waitcnt vmcnt(31)
	v_mov_b32_e32 v26, v192
	v_mov_b32_e32 v27, v193
	v_lshlrev_b32_e32 v28, 16, v26
	v_and_b32_e32 v26, 0xffff0000, v26
	v_mul_f32_e32 v22, v22, v28
	v_mul_f32_e32 v23, v23, v26
	v_mul_f32_e32 v22, v0, v22
	v_mul_f32_e32 v23, v0, v23
	v_cvt_pk_bf16_f32 v22, v22, v23
	v_lshlrev_b32_e32 v23, 16, v27
	v_mul_f32_e32 v23, v24, v23
	v_and_b32_e32 v24, 0xffff0000, v27
	v_mul_f32_e32 v23, v0, v23
	v_mul_f32_e32 v24, v25, v24
	v_mul_f32_e32 v24, v0, v24
	v_cvt_pk_bf16_f32 v23, v23, v24
	global_store_dwordx2 v[34:35], v[22:23], off offset:64
	s_waitcnt vmcnt(31)
	v_mov_b32_e32 v22, v194
	v_mov_b32_e32 v23, v195
	v_lshlrev_b32_e32 v24, 16, v22
	v_and_b32_e32 v22, 0xffff0000, v22
	v_mul_f32_e32 v18, v18, v24
	v_mul_f32_e32 v19, v19, v22
	v_mul_f32_e32 v18, v0, v18
	v_mul_f32_e32 v19, v0, v19
	v_cvt_pk_bf16_f32 v18, v18, v19
	v_lshlrev_b32_e32 v19, 16, v23
	v_mul_f32_e32 v19, v20, v19
	v_and_b32_e32 v20, 0xffff0000, v23
	v_mul_f32_e32 v19, v0, v19
	v_mul_f32_e32 v20, v21, v20
	v_mul_f32_e32 v0, v0, v20
	v_cvt_pk_bf16_f32 v19, v19, v0
	global_store_dwordx2 v[34:35], v[18:19], off offset:96
	ds_read2_b32 v[18:19], v136 offset0:112 offset1:240
	s_waitcnt lgkmcnt(0)
	v_add_f32_e32 v0, 0, v18
	v_add_f32_e32 v0, v0, v19
	ds_read2st64_b32 v[18:19], v84 offset0:5 offset1:7
	s_waitcnt lgkmcnt(0)
	v_add_f32_e32 v0, v0, v18
	v_add_f32_e32 v0, v0, v19
	ds_read2st64_b32 v[18:19], v84 offset0:9 offset1:11
	s_waitcnt lgkmcnt(0)
	v_add_f32_e32 v0, v0, v18
	v_add_f32_e32 v0, v0, v19
	ds_read2st64_b32 v[18:19], v84 offset0:13 offset1:15
	s_waitcnt lgkmcnt(0)
	v_add_f32_e32 v0, v0, v18
	v_add_f32_e32 v0, v0, v19
	v_fmamk_f32 v0, v0, 0x3b000000, v207
	v_cmp_gt_f32_e32 vcc, s87, v0
	v_mul_f32_e32 v18, 0x4b800000, v0
	s_nop 0
	v_cndmask_b32_e32 v0, v0, v18, vcc
	v_rsq_f32_e32 v0, v0
	s_nop 0
	v_mul_f32_e32 v18, 0x45800000, v0
	v_cndmask_b32_e32 v0, v0, v18, vcc
	v_lshlrev_b64 v[18:19], 13, v[130:131]
	v_lshl_add_u64 v[18:19], v[132:133], 0, v[18:19]
	s_waitcnt vmcnt(31)
	v_mov_b32_e32 v20, v196
	v_mov_b32_e32 v21, v197
	v_lshlrev_b32_e32 v22, 16, v20
	v_and_b32_e32 v20, 0xffff0000, v20
	v_mul_f32_e32 v14, v14, v22
	v_mul_f32_e32 v15, v15, v20
	v_mul_f32_e32 v14, v14, v0
	v_mul_f32_e32 v15, v15, v0
	v_cvt_pk_bf16_f32 v14, v14, v15
	v_lshlrev_b32_e32 v15, 16, v21
	v_mul_f32_e32 v15, v16, v15
	v_and_b32_e32 v16, 0xffff0000, v21
	v_mul_f32_e32 v15, v15, v0
	v_mul_f32_e32 v16, v17, v16
	v_mul_f32_e32 v16, v16, v0
	v_cvt_pk_bf16_f32 v15, v15, v16
	global_store_dwordx2 v[18:19], v[14:15], off
	s_waitcnt vmcnt(31)
	v_mov_b32_e32 v14, v198
	v_mov_b32_e32 v15, v199
	v_lshlrev_b32_e32 v16, 16, v14
	v_and_b32_e32 v14, 0xffff0000, v14
	v_mul_f32_e32 v10, v10, v16
	v_mul_f32_e32 v11, v11, v14
	v_mul_f32_e32 v10, v0, v10
	v_mul_f32_e32 v11, v0, v11
	v_cvt_pk_bf16_f32 v10, v10, v11
	v_lshlrev_b32_e32 v11, 16, v15
	v_mul_f32_e32 v11, v12, v11
	v_and_b32_e32 v12, 0xffff0000, v15
	v_mul_f32_e32 v11, v0, v11
	v_mul_f32_e32 v12, v13, v12
	v_mul_f32_e32 v12, v0, v12
	v_cvt_pk_bf16_f32 v11, v11, v12
	global_store_dwordx2 v[18:19], v[10:11], off offset:32
	s_waitcnt vmcnt(31)
	v_mov_b32_e32 v10, v200
	v_mov_b32_e32 v11, v201
	v_lshlrev_b32_e32 v12, 16, v10
	v_and_b32_e32 v10, 0xffff0000, v10
	v_mul_f32_e32 v6, v6, v12
	v_mul_f32_e32 v7, v7, v10
	v_mul_f32_e32 v6, v0, v6
	v_mul_f32_e32 v7, v0, v7
	v_cvt_pk_bf16_f32 v6, v6, v7
	v_lshlrev_b32_e32 v7, 16, v11
	v_mul_f32_e32 v7, v8, v7
	v_and_b32_e32 v8, 0xffff0000, v11
	v_mul_f32_e32 v7, v0, v7
	v_mul_f32_e32 v8, v9, v8
	v_mul_f32_e32 v8, v0, v8
	v_cvt_pk_bf16_f32 v7, v7, v8
	global_store_dwordx2 v[18:19], v[6:7], off offset:64
	s_waitcnt vmcnt(31)
	v_mov_b32_e32 v6, v202
	v_mov_b32_e32 v7, v203
	v_lshlrev_b32_e32 v8, 16, v6
	v_and_b32_e32 v6, 0xffff0000, v6
	v_mul_f32_e32 v2, v2, v8
	v_mul_f32_e32 v3, v3, v6
	v_mul_f32_e32 v2, v0, v2
	v_mul_f32_e32 v3, v0, v3
	v_cvt_pk_bf16_f32 v2, v2, v3
	v_lshlrev_b32_e32 v3, 16, v7
	v_mul_f32_e32 v3, v4, v3
	v_and_b32_e32 v4, 0xffff0000, v7
	v_mul_f32_e32 v3, v0, v3
	v_mul_f32_e32 v4, v5, v4
	v_mul_f32_e32 v0, v0, v4
	v_cvt_pk_bf16_f32 v3, v3, v0
	global_store_dwordx2 v[18:19], v[2:3], off offset:96
	s_waitcnt lgkmcnt(0)
	s_barrier
	s_cbranch_scc0 .LBB0_734

.LBB0_958:
	v_lshl_add_u32 v140, s2, 8, v142
	v_ashrrev_i32_e32 v141, 31, v140
	v_lshl_add_u64 v[148:149], v[140:141], 2, s[4:5]
	global_load_dword v152, v[148:149], off
	global_load_dword v153, v[148:149], off offset:64
	global_load_dword v154, v[148:149], off offset:128
	global_load_dword v155, v[148:149], off offset:192
	global_load_dword v156, v[148:149], off offset:512
	global_load_dword v157, v[148:149], off offset:576
	global_load_dword v158, v[148:149], off offset:640
	global_load_dword v159, v[148:149], off offset:704
	v_lshl_or_b32 v146, s6, 8, v144
	v_readlane_b32 s6, v254, 30
	v_ashrrev_i32_e32 v147, 31, v146
	v_readlane_b32 s7, v254, 31
	s_mov_b64 s[30:31], -1
	s_mov_b32 s56, 0x10000
	s_mov_b32 s57, 0x20000
	s_waitcnt vmcnt(0) lgkmcnt(0)
	v_mov_b32_e32 v148, v152
	v_fmamk_f32 v148, v148, 0x3a000000, v207
	v_cmp_gt_f32_e32 vcc, s87, v148
	v_mul_f32_e32 v149, 0x4b800000, v148
	s_nop 0
	v_cndmask_b32_e32 v148, v148, v149, vcc
	v_rsq_f32_e32 v148, v148
	s_nop 0
	v_mul_f32_e32 v149, 0x45800000, v148
	v_cndmask_b32_e32 v148, v148, v149, vcc
	v_pk_mul_f32 v[126:127], v[126:127], v[148:149] op_sel_hi:[1,0]
	v_pk_mul_f32 v[124:125], v[124:125], v[148:149] op_sel_hi:[1,0]
	v_pk_mul_f32 v[122:123], v[122:123], v[148:149] op_sel_hi:[1,0]
	v_pk_mul_f32 v[128:129], v[128:129], v[148:149] op_sel_hi:[1,0]
	v_max_f32_e32 v126, 0, v126
	v_max_f32_e32 v122, 0, v122
	v_max_f32_e32 v123, 0, v123
	v_max_f32_e32 v124, 0, v124
	v_mul_f32_e32 v126, v126, v126
	v_mul_f32_e32 v122, v122, v122
	v_max_f32_e32 v127, 0, v127
	v_mul_f32_e32 v123, v123, v123
	v_max_f32_e32 v128, 0, v128
	v_mul_f32_e32 v149, v124, v124
	v_max_f32_e32 v124, 0, v129
	v_max_f32_e32 v125, 0, v125
	v_mul_f32_e32 v127, v127, v127
	v_mul_f32_e32 v128, v128, v128
	v_mul_f32_e32 v129, v124, v124
	v_mul_f32_e32 v150, v125, v125
	v_cvt_pk_bf16_f32 v124, v126, v127
	v_cvt_pk_bf16_f32 v125, v128, v129
	v_cvt_pk_bf16_f32 v126, v122, v123
	v_lshlrev_b64 v[122:123], 14, v[140:141]
	v_lshl_add_u64 v[128:129], s[6:7], 0, v[122:123]
	v_lshlrev_b64 v[122:123], 1, v[146:147]
	v_pk_mul_f32 v[114:115], v[114:115], v[148:149] op_sel_hi:[1,0]
	v_lshl_add_u64 v[128:129], v[128:129], 0, v[122:123]
	v_pk_mul_f32 v[118:119], v[118:119], v[148:149] op_sel_hi:[1,0]
	v_pk_mul_f32 v[116:117], v[116:117], v[148:149] op_sel_hi:[1,0]
	v_max_f32_e32 v114, 0, v114
	v_cvt_pk_bf16_f32 v127, v149, v150
	global_store_dwordx4 v[128:129], v[124:127], off
	v_pk_mul_f32 v[120:121], v[120:121], v[148:149] op_sel_hi:[1,0]
	v_max_f32_e32 v115, 0, v115
	v_mul_f32_e32 v124, v114, v114
	v_max_f32_e32 v114, 0, v119
	v_max_f32_e32 v116, 0, v116
	v_max_f32_e32 v118, 0, v118
	v_mul_f32_e32 v114, v114, v114
	v_mul_f32_e32 v119, v115, v115
	v_max_f32_e32 v115, 0, v120
	v_mul_f32_e32 v120, v116, v116
	v_max_f32_e32 v116, 0, v121
	v_max_f32_e32 v117, 0, v117
	v_mul_f32_e32 v118, v118, v118
	v_mul_f32_e32 v115, v115, v115
	v_mul_f32_e32 v116, v116, v116
	v_mul_f32_e32 v117, v117, v117
	v_cvt_pk_bf16_f32 v114, v118, v114
	v_cvt_pk_bf16_f32 v115, v115, v116
	v_cvt_pk_bf16_f32 v116, v124, v119
	v_cvt_pk_bf16_f32 v117, v120, v117
	global_store_dwordx4 v[128:129], v[114:117], off offset:256
	s_nop 1
	v_or_b32_e32 v114, 16, v140
	v_ashrrev_i32_e32 v115, 31, v114
	v_lshl_add_u64 v[116:117], v[114:115], 2, s[4:5]
	v_mov_b32_e32 v116, v153
	v_fmamk_f32 v116, v116, 0x3a000000, v207
	v_cmp_gt_f32_e32 vcc, s87, v116
	v_mul_f32_e32 v117, 0x4b800000, v116
	s_nop 0
	v_cndmask_b32_e32 v116, v116, v117, vcc
	v_rsq_f32_e32 v116, v116
	s_nop 0
	v_mul_f32_e32 v117, 0x45800000, v116
	v_cndmask_b32_e32 v116, v116, v117, vcc
	v_pk_mul_f32 v[108:109], v[108:109], v[116:117] op_sel_hi:[1,0]
	v_pk_mul_f32 v[106:107], v[106:107], v[116:117] op_sel_hi:[1,0]
	v_pk_mul_f32 v[112:113], v[112:113], v[116:117] op_sel_hi:[1,0]
	v_pk_mul_f32 v[110:111], v[110:111], v[116:117] op_sel_hi:[1,0]
	v_max_f32_e32 v106, 0, v106
	v_max_f32_e32 v107, 0, v107
	v_max_f32_e32 v108, 0, v108
	v_max_f32_e32 v110, 0, v110
	v_mul_f32_e32 v117, v106, v106
	v_max_f32_e32 v106, 0, v111
	v_mul_f32_e32 v111, v107, v107
	v_max_f32_e32 v107, 0, v112
	v_mul_f32_e32 v112, v108, v108
	v_max_f32_e32 v108, 0, v113
	v_mul_f32_e32 v110, v110, v110
	v_mul_f32_e32 v106, v106, v106
	v_mul_f32_e32 v107, v107, v107
	v_mul_f32_e32 v108, v108, v108
	v_cvt_pk_bf16_f32 v106, v110, v106
	v_cvt_pk_bf16_f32 v107, v107, v108
	v_cvt_pk_bf16_f32 v108, v117, v111
	v_lshlrev_b64 v[110:111], 14, v[114:115]
	v_max_f32_e32 v109, 0, v109
	v_lshl_add_u64 v[110:111], s[6:7], 0, v[110:111]
	v_pk_mul_f32 v[98:99], v[98:99], v[116:117] op_sel_hi:[1,0]
	v_mul_f32_e32 v109, v109, v109
	v_lshl_add_u64 v[110:111], v[110:111], 0, v[122:123]
	v_pk_mul_f32 v[102:103], v[102:103], v[116:117] op_sel_hi:[1,0]
	v_pk_mul_f32 v[100:101], v[100:101], v[116:117] op_sel_hi:[1,0]
	v_max_f32_e32 v98, 0, v98
	v_cvt_pk_bf16_f32 v109, v112, v109
	global_store_dwordx4 v[110:111], v[106:109], off
	v_pk_mul_f32 v[104:105], v[104:105], v[116:117] op_sel_hi:[1,0]
	v_max_f32_e32 v99, 0, v99
	v_mul_f32_e32 v106, v98, v98
	v_max_f32_e32 v98, 0, v103
	v_max_f32_e32 v100, 0, v100
	v_max_f32_e32 v102, 0, v102
	v_mul_f32_e32 v98, v98, v98
	v_mul_f32_e32 v103, v99, v99
	v_max_f32_e32 v99, 0, v104
	v_mul_f32_e32 v104, v100, v100
	v_max_f32_e32 v100, 0, v105
	v_max_f32_e32 v101, 0, v101
	v_mul_f32_e32 v102, v102, v102
	v_mul_f32_e32 v99, v99, v99
	v_mul_f32_e32 v100, v100, v100
	v_mul_f32_e32 v101, v101, v101
	v_cvt_pk_bf16_f32 v98, v102, v98
	v_cvt_pk_bf16_f32 v99, v99, v100
	v_cvt_pk_bf16_f32 v100, v106, v103
	v_cvt_pk_bf16_f32 v101, v104, v101
	global_store_dwordx4 v[110:111], v[98:101], off offset:256
	s_nop 1
	v_or_b32_e32 v98, 32, v140
	v_ashrrev_i32_e32 v99, 31, v98
	v_lshl_add_u64 v[100:101], v[98:99], 2, s[4:5]
	v_mov_b32_e32 v100, v154
	v_fmamk_f32 v100, v100, 0x3a000000, v207
	v_cmp_gt_f32_e32 vcc, s87, v100
	v_mul_f32_e32 v101, 0x4b800000, v100
	s_nop 0
	v_cndmask_b32_e32 v100, v100, v101, vcc
	v_rsq_f32_e32 v100, v100
	s_nop 0
	v_mul_f32_e32 v101, 0x45800000, v100
	v_cndmask_b32_e32 v100, v100, v101, vcc
	v_pk_mul_f32 v[92:93], v[92:93], v[100:101] op_sel_hi:[1,0]
	v_pk_mul_f32 v[90:91], v[90:91], v[100:101] op_sel_hi:[1,0]
	v_pk_mul_f32 v[96:97], v[96:97], v[100:101] op_sel_hi:[1,0]
	v_pk_mul_f32 v[94:95], v[94:95], v[100:101] op_sel_hi:[1,0]
	v_max_f32_e32 v90, 0, v90
	v_max_f32_e32 v91, 0, v91
	v_max_f32_e32 v92, 0, v92
	v_max_f32_e32 v94, 0, v94
	v_mul_f32_e32 v101, v90, v90
	v_max_f32_e32 v90, 0, v95
	v_mul_f32_e32 v95, v91, v91
	v_max_f32_e32 v91, 0, v96
	v_mul_f32_e32 v96, v92, v92
	v_max_f32_e32 v92, 0, v97
	v_mul_f32_e32 v94, v94, v94
	v_mul_f32_e32 v90, v90, v90
	v_mul_f32_e32 v91, v91, v91
	v_mul_f32_e32 v92, v92, v92
	v_cvt_pk_bf16_f32 v90, v94, v90
	v_cvt_pk_bf16_f32 v91, v91, v92
	v_cvt_pk_bf16_f32 v92, v101, v95
	v_lshlrev_b64 v[94:95], 14, v[98:99]
	v_max_f32_e32 v93, 0, v93
	v_lshl_add_u64 v[94:95], s[6:7], 0, v[94:95]
	v_pk_mul_f32 v[82:83], v[82:83], v[100:101] op_sel_hi:[1,0]
	v_mul_f32_e32 v93, v93, v93
	v_lshl_add_u64 v[94:95], v[94:95], 0, v[122:123]
	v_pk_mul_f32 v[86:87], v[86:87], v[100:101] op_sel_hi:[1,0]
	v_pk_mul_f32 v[84:85], v[84:85], v[100:101] op_sel_hi:[1,0]
	v_max_f32_e32 v82, 0, v82
	v_cvt_pk_bf16_f32 v93, v96, v93
	global_store_dwordx4 v[94:95], v[90:93], off
	v_pk_mul_f32 v[88:89], v[88:89], v[100:101] op_sel_hi:[1,0]
	v_max_f32_e32 v83, 0, v83
	v_mul_f32_e32 v90, v82, v82
	v_max_f32_e32 v82, 0, v87
	v_max_f32_e32 v84, 0, v84
	v_max_f32_e32 v86, 0, v86
	v_mul_f32_e32 v82, v82, v82
	v_mul_f32_e32 v87, v83, v83
	v_max_f32_e32 v83, 0, v88
	v_mul_f32_e32 v88, v84, v84
	v_max_f32_e32 v84, 0, v89
	v_max_f32_e32 v85, 0, v85
	v_mul_f32_e32 v86, v86, v86
	v_mul_f32_e32 v83, v83, v83
	v_mul_f32_e32 v84, v84, v84
	v_mul_f32_e32 v85, v85, v85
	v_cvt_pk_bf16_f32 v82, v86, v82
	v_cvt_pk_bf16_f32 v83, v83, v84
	v_cvt_pk_bf16_f32 v84, v90, v87
	v_cvt_pk_bf16_f32 v85, v88, v85
	global_store_dwordx4 v[94:95], v[82:85], off offset:256
	s_nop 1
	v_or_b32_e32 v82, 48, v140
	v_ashrrev_i32_e32 v83, 31, v82
	v_lshl_add_u64 v[84:85], v[82:83], 2, s[4:5]
	v_mov_b32_e32 v84, v155
	v_fmamk_f32 v84, v84, 0x3a000000, v207
	v_cmp_gt_f32_e32 vcc, s87, v84
	v_mul_f32_e32 v85, 0x4b800000, v84
	s_nop 0
	v_cndmask_b32_e32 v84, v84, v85, vcc
	v_rsq_f32_e32 v84, v84
	s_nop 0
	v_mul_f32_e32 v85, 0x45800000, v84
	v_cndmask_b32_e32 v84, v84, v85, vcc
	v_pk_mul_f32 v[76:77], v[76:77], v[84:85] op_sel_hi:[1,0]
	v_pk_mul_f32 v[74:75], v[74:75], v[84:85] op_sel_hi:[1,0]
	v_pk_mul_f32 v[80:81], v[80:81], v[84:85] op_sel_hi:[1,0]
	v_pk_mul_f32 v[78:79], v[78:79], v[84:85] op_sel_hi:[1,0]
	v_max_f32_e32 v74, 0, v74
	v_max_f32_e32 v75, 0, v75
	v_max_f32_e32 v76, 0, v76
	v_max_f32_e32 v78, 0, v78
	v_mul_f32_e32 v85, v74, v74
	v_max_f32_e32 v74, 0, v79
	v_mul_f32_e32 v79, v75, v75
	v_max_f32_e32 v75, 0, v80
	v_mul_f32_e32 v80, v76, v76
	v_max_f32_e32 v76, 0, v81
	v_mul_f32_e32 v78, v78, v78
	v_mul_f32_e32 v74, v74, v74
	v_mul_f32_e32 v75, v75, v75
	v_mul_f32_e32 v76, v76, v76
	v_cvt_pk_bf16_f32 v74, v78, v74
	v_cvt_pk_bf16_f32 v75, v75, v76
	v_cvt_pk_bf16_f32 v76, v85, v79
	v_lshlrev_b64 v[78:79], 14, v[82:83]
	v_max_f32_e32 v77, 0, v77
	v_lshl_add_u64 v[78:79], s[6:7], 0, v[78:79]
	v_pk_mul_f32 v[66:67], v[66:67], v[84:85] op_sel_hi:[1,0]
	v_mul_f32_e32 v77, v77, v77
	v_lshl_add_u64 v[78:79], v[78:79], 0, v[122:123]
	v_pk_mul_f32 v[70:71], v[70:71], v[84:85] op_sel_hi:[1,0]
	v_pk_mul_f32 v[68:69], v[68:69], v[84:85] op_sel_hi:[1,0]
	v_max_f32_e32 v66, 0, v66
	v_cvt_pk_bf16_f32 v77, v80, v77
	global_store_dwordx4 v[78:79], v[74:77], off
	v_pk_mul_f32 v[72:73], v[72:73], v[84:85] op_sel_hi:[1,0]
	v_max_f32_e32 v67, 0, v67
	v_mul_f32_e32 v74, v66, v66
	v_max_f32_e32 v66, 0, v71
	v_max_f32_e32 v68, 0, v68
	v_max_f32_e32 v70, 0, v70
	v_mul_f32_e32 v66, v66, v66
	v_mul_f32_e32 v71, v67, v67
	v_max_f32_e32 v67, 0, v72
	v_mul_f32_e32 v72, v68, v68
	v_max_f32_e32 v68, 0, v73
	v_max_f32_e32 v69, 0, v69
	v_mul_f32_e32 v70, v70, v70
	v_mul_f32_e32 v67, v67, v67
	v_mul_f32_e32 v68, v68, v68
	v_mul_f32_e32 v69, v69, v69
	v_cvt_pk_bf16_f32 v66, v70, v66
	v_cvt_pk_bf16_f32 v67, v67, v68
	v_cvt_pk_bf16_f32 v68, v74, v71
	v_cvt_pk_bf16_f32 v69, v72, v69
	global_store_dwordx4 v[78:79], v[66:69], off offset:256
	s_nop 1
	v_add_u32_e32 v66, 0x80, v140
	v_ashrrev_i32_e32 v67, 31, v66
	v_lshl_add_u64 v[68:69], v[66:67], 2, s[4:5]
	v_mov_b32_e32 v68, v156
	v_fmamk_f32 v68, v68, 0x3a000000, v207
	v_cmp_gt_f32_e32 vcc, s87, v68
	v_mul_f32_e32 v69, 0x4b800000, v68
	s_nop 0
	v_cndmask_b32_e32 v68, v68, v69, vcc
	v_rsq_f32_e32 v68, v68
	s_nop 0
	v_mul_f32_e32 v69, 0x45800000, v68
	v_cndmask_b32_e32 v68, v68, v69, vcc
	v_pk_mul_f32 v[60:61], v[60:61], v[68:69] op_sel_hi:[1,0]
	v_pk_mul_f32 v[58:59], v[58:59], v[68:69] op_sel_hi:[1,0]
	v_pk_mul_f32 v[64:65], v[64:65], v[68:69] op_sel_hi:[1,0]
	v_pk_mul_f32 v[62:63], v[62:63], v[68:69] op_sel_hi:[1,0]
	v_max_f32_e32 v58, 0, v58
	v_max_f32_e32 v59, 0, v59
	v_max_f32_e32 v60, 0, v60
	v_max_f32_e32 v62, 0, v62
	v_mul_f32_e32 v69, v58, v58
	v_max_f32_e32 v58, 0, v63
	v_mul_f32_e32 v63, v59, v59
	v_max_f32_e32 v59, 0, v64
	v_mul_f32_e32 v64, v60, v60
	v_max_f32_e32 v60, 0, v65
	v_mul_f32_e32 v62, v62, v62
	v_mul_f32_e32 v58, v58, v58
	v_mul_f32_e32 v59, v59, v59
	v_mul_f32_e32 v60, v60, v60
	v_cvt_pk_bf16_f32 v58, v62, v58
	v_cvt_pk_bf16_f32 v59, v59, v60
	v_cvt_pk_bf16_f32 v60, v69, v63
	v_lshlrev_b64 v[62:63], 14, v[66:67]
	v_max_f32_e32 v61, 0, v61
	v_lshl_add_u64 v[62:63], s[6:7], 0, v[62:63]
	v_pk_mul_f32 v[50:51], v[50:51], v[68:69] op_sel_hi:[1,0]
	v_mul_f32_e32 v61, v61, v61
	v_lshl_add_u64 v[62:63], v[62:63], 0, v[122:123]
	v_pk_mul_f32 v[54:55], v[54:55], v[68:69] op_sel_hi:[1,0]
	v_pk_mul_f32 v[52:53], v[52:53], v[68:69] op_sel_hi:[1,0]
	v_max_f32_e32 v50, 0, v50
	v_cvt_pk_bf16_f32 v61, v64, v61
	global_store_dwordx4 v[62:63], v[58:61], off
	v_pk_mul_f32 v[56:57], v[56:57], v[68:69] op_sel_hi:[1,0]
	v_max_f32_e32 v51, 0, v51
	v_mul_f32_e32 v58, v50, v50
	v_max_f32_e32 v50, 0, v55
	v_max_f32_e32 v52, 0, v52
	v_max_f32_e32 v54, 0, v54
	v_mul_f32_e32 v50, v50, v50
	v_mul_f32_e32 v55, v51, v51
	v_max_f32_e32 v51, 0, v56
	v_mul_f32_e32 v56, v52, v52
	v_max_f32_e32 v52, 0, v57
	v_max_f32_e32 v53, 0, v53
	v_mul_f32_e32 v54, v54, v54
	v_mul_f32_e32 v51, v51, v51
	v_mul_f32_e32 v52, v52, v52
	v_mul_f32_e32 v53, v53, v53
	v_cvt_pk_bf16_f32 v50, v54, v50
	v_cvt_pk_bf16_f32 v51, v51, v52
	v_cvt_pk_bf16_f32 v52, v58, v55
	v_cvt_pk_bf16_f32 v53, v56, v53
	global_store_dwordx4 v[62:63], v[50:53], off offset:256
	s_nop 1
	v_add_u32_e32 v50, 0x90, v140
	v_ashrrev_i32_e32 v51, 31, v50
	v_lshl_add_u64 v[52:53], v[50:51], 2, s[4:5]
	v_mov_b32_e32 v52, v157
	v_fmamk_f32 v52, v52, 0x3a000000, v207
	v_cmp_gt_f32_e32 vcc, s87, v52
	v_mul_f32_e32 v53, 0x4b800000, v52
	s_nop 0
	v_cndmask_b32_e32 v52, v52, v53, vcc
	v_rsq_f32_e32 v52, v52
	s_nop 0
	v_mul_f32_e32 v53, 0x45800000, v52
	v_cndmask_b32_e32 v52, v52, v53, vcc
	v_pk_mul_f32 v[44:45], v[44:45], v[52:53] op_sel_hi:[1,0]
	v_pk_mul_f32 v[42:43], v[42:43], v[52:53] op_sel_hi:[1,0]
	v_pk_mul_f32 v[48:49], v[48:49], v[52:53] op_sel_hi:[1,0]
	v_pk_mul_f32 v[46:47], v[46:47], v[52:53] op_sel_hi:[1,0]
	v_max_f32_e32 v42, 0, v42
	v_max_f32_e32 v43, 0, v43
	v_max_f32_e32 v44, 0, v44
	v_max_f32_e32 v46, 0, v46
	v_mul_f32_e32 v53, v42, v42
	v_max_f32_e32 v42, 0, v47
	v_mul_f32_e32 v47, v43, v43
	v_max_f32_e32 v43, 0, v48
	v_mul_f32_e32 v48, v44, v44
	v_max_f32_e32 v44, 0, v49
	v_mul_f32_e32 v46, v46, v46
	v_mul_f32_e32 v42, v42, v42
	v_mul_f32_e32 v43, v43, v43
	v_mul_f32_e32 v44, v44, v44
	v_cvt_pk_bf16_f32 v42, v46, v42
	v_cvt_pk_bf16_f32 v43, v43, v44
	v_cvt_pk_bf16_f32 v44, v53, v47
	v_lshlrev_b64 v[46:47], 14, v[50:51]
	v_max_f32_e32 v45, 0, v45
	v_lshl_add_u64 v[46:47], s[6:7], 0, v[46:47]
	v_pk_mul_f32 v[34:35], v[34:35], v[52:53] op_sel_hi:[1,0]
	v_mul_f32_e32 v45, v45, v45
	v_lshl_add_u64 v[46:47], v[46:47], 0, v[122:123]
	v_pk_mul_f32 v[38:39], v[38:39], v[52:53] op_sel_hi:[1,0]
	v_pk_mul_f32 v[36:37], v[36:37], v[52:53] op_sel_hi:[1,0]
	v_max_f32_e32 v34, 0, v34
	v_cvt_pk_bf16_f32 v45, v48, v45
	global_store_dwordx4 v[46:47], v[42:45], off
	v_pk_mul_f32 v[40:41], v[40:41], v[52:53] op_sel_hi:[1,0]
	v_max_f32_e32 v35, 0, v35
	v_mul_f32_e32 v42, v34, v34
	v_max_f32_e32 v34, 0, v39
	v_max_f32_e32 v36, 0, v36
	v_max_f32_e32 v38, 0, v38
	v_mul_f32_e32 v34, v34, v34
	v_mul_f32_e32 v39, v35, v35
	v_max_f32_e32 v35, 0, v40
	v_mul_f32_e32 v40, v36, v36
	v_max_f32_e32 v36, 0, v41
	v_max_f32_e32 v37, 0, v37
	v_mul_f32_e32 v38, v38, v38
	v_mul_f32_e32 v35, v35, v35
	v_mul_f32_e32 v36, v36, v36
	v_mul_f32_e32 v37, v37, v37
	v_cvt_pk_bf16_f32 v34, v38, v34
	v_cvt_pk_bf16_f32 v35, v35, v36
	v_cvt_pk_bf16_f32 v36, v42, v39
	v_cvt_pk_bf16_f32 v37, v40, v37
	global_store_dwordx4 v[46:47], v[34:37], off offset:256
	s_nop 1
	v_add_u32_e32 v34, 0xa0, v140
	v_ashrrev_i32_e32 v35, 31, v34
	v_lshl_add_u64 v[36:37], v[34:35], 2, s[4:5]
	v_mov_b32_e32 v36, v158
	v_fmamk_f32 v36, v36, 0x3a000000, v207
	v_cmp_gt_f32_e32 vcc, s87, v36
	v_mul_f32_e32 v37, 0x4b800000, v36
	s_nop 0
	v_cndmask_b32_e32 v36, v36, v37, vcc
	v_rsq_f32_e32 v36, v36
	s_nop 0
	v_mul_f32_e32 v37, 0x45800000, v36
	v_cndmask_b32_e32 v36, v36, v37, vcc
	v_pk_mul_f32 v[28:29], v[28:29], v[36:37] op_sel_hi:[1,0]
	v_pk_mul_f32 v[26:27], v[26:27], v[36:37] op_sel_hi:[1,0]
	v_pk_mul_f32 v[32:33], v[32:33], v[36:37] op_sel_hi:[1,0]
	v_pk_mul_f32 v[30:31], v[30:31], v[36:37] op_sel_hi:[1,0]
	v_max_f32_e32 v26, 0, v26
	v_max_f32_e32 v27, 0, v27
	v_max_f32_e32 v28, 0, v28
	v_max_f32_e32 v30, 0, v30
	v_mul_f32_e32 v37, v26, v26
	v_max_f32_e32 v26, 0, v31
	v_mul_f32_e32 v31, v27, v27
	v_max_f32_e32 v27, 0, v32
	v_mul_f32_e32 v32, v28, v28
	v_max_f32_e32 v28, 0, v33
	v_mul_f32_e32 v30, v30, v30
	v_mul_f32_e32 v26, v26, v26
	v_mul_f32_e32 v27, v27, v27
	v_mul_f32_e32 v28, v28, v28
	v_cvt_pk_bf16_f32 v26, v30, v26
	v_cvt_pk_bf16_f32 v27, v27, v28
	v_cvt_pk_bf16_f32 v28, v37, v31
	v_lshlrev_b64 v[30:31], 14, v[34:35]
	v_max_f32_e32 v29, 0, v29
	v_lshl_add_u64 v[30:31], s[6:7], 0, v[30:31]
	v_pk_mul_f32 v[18:19], v[18:19], v[36:37] op_sel_hi:[1,0]
	v_mul_f32_e32 v29, v29, v29
	v_lshl_add_u64 v[30:31], v[30:31], 0, v[122:123]
	v_pk_mul_f32 v[22:23], v[22:23], v[36:37] op_sel_hi:[1,0]
	v_pk_mul_f32 v[20:21], v[20:21], v[36:37] op_sel_hi:[1,0]
	v_max_f32_e32 v18, 0, v18
	v_cvt_pk_bf16_f32 v29, v32, v29
	global_store_dwordx4 v[30:31], v[26:29], off
	v_pk_mul_f32 v[24:25], v[24:25], v[36:37] op_sel_hi:[1,0]
	v_max_f32_e32 v19, 0, v19
	v_mul_f32_e32 v26, v18, v18
	v_max_f32_e32 v18, 0, v23
	v_max_f32_e32 v20, 0, v20
	v_max_f32_e32 v22, 0, v22
	v_mul_f32_e32 v18, v18, v18
	v_mul_f32_e32 v23, v19, v19
	v_max_f32_e32 v19, 0, v24
	v_mul_f32_e32 v24, v20, v20
	v_max_f32_e32 v20, 0, v25
	v_max_f32_e32 v21, 0, v21
	v_mul_f32_e32 v22, v22, v22
	v_mul_f32_e32 v19, v19, v19
	v_mul_f32_e32 v20, v20, v20
	v_mul_f32_e32 v21, v21, v21
	v_cvt_pk_bf16_f32 v18, v22, v18
	v_cvt_pk_bf16_f32 v19, v19, v20
	v_cvt_pk_bf16_f32 v20, v26, v23
	v_cvt_pk_bf16_f32 v21, v24, v21
	global_store_dwordx4 v[30:31], v[18:21], off offset:256
	s_nop 1
	v_add_u32_e32 v18, 0xb0, v140
	v_ashrrev_i32_e32 v19, 31, v18
	v_lshl_add_u64 v[20:21], v[18:19], 2, s[4:5]
	v_mov_b32_e32 v20, v159
	v_fmamk_f32 v20, v20, 0x3a000000, v207
	v_cmp_gt_f32_e32 vcc, s87, v20
	v_mul_f32_e32 v21, 0x4b800000, v20
	s_nop 0
	v_cndmask_b32_e32 v20, v20, v21, vcc
	v_rsq_f32_e32 v20, v20
	s_nop 0
	v_mul_f32_e32 v21, 0x45800000, v20
	v_cndmask_b32_e32 v20, v20, v21, vcc
	v_pk_mul_f32 v[12:13], v[12:13], v[20:21] op_sel_hi:[1,0]
	v_pk_mul_f32 v[10:11], v[10:11], v[20:21] op_sel_hi:[1,0]
	v_pk_mul_f32 v[16:17], v[16:17], v[20:21] op_sel_hi:[1,0]
	v_pk_mul_f32 v[14:15], v[14:15], v[20:21] op_sel_hi:[1,0]
	v_max_f32_e32 v10, 0, v10
	v_max_f32_e32 v11, 0, v11
	v_max_f32_e32 v12, 0, v12
	v_max_f32_e32 v14, 0, v14
	v_mul_f32_e32 v21, v10, v10
	v_max_f32_e32 v10, 0, v15
	v_mul_f32_e32 v15, v11, v11
	v_max_f32_e32 v11, 0, v16
	v_mul_f32_e32 v16, v12, v12
	v_max_f32_e32 v12, 0, v17
	v_mul_f32_e32 v14, v14, v14
	v_mul_f32_e32 v10, v10, v10
	v_mul_f32_e32 v11, v11, v11
	v_mul_f32_e32 v12, v12, v12
	v_cvt_pk_bf16_f32 v10, v14, v10
	v_cvt_pk_bf16_f32 v11, v11, v12
	v_cvt_pk_bf16_f32 v12, v21, v15
	v_lshlrev_b64 v[14:15], 14, v[18:19]
	v_max_f32_e32 v13, 0, v13
	v_lshl_add_u64 v[14:15], s[6:7], 0, v[14:15]
	v_pk_mul_f32 v[4:5], v[4:5], v[20:21] op_sel_hi:[1,0]
	v_pk_mul_f32 v[2:3], v[2:3], v[20:21] op_sel_hi:[1,0]
	v_mul_f32_e32 v13, v13, v13
	v_lshl_add_u64 v[14:15], v[14:15], 0, v[122:123]
	v_pk_mul_f32 v[8:9], v[8:9], v[20:21] op_sel_hi:[1,0]
	v_pk_mul_f32 v[6:7], v[6:7], v[20:21] op_sel_hi:[1,0]
	v_max_f32_e32 v2, 0, v2
	v_max_f32_e32 v3, 0, v3
	v_max_f32_e32 v4, 0, v4
	v_cvt_pk_bf16_f32 v13, v16, v13
	global_store_dwordx4 v[14:15], v[10:13], off
	v_max_f32_e32 v5, 0, v5
	v_max_f32_e32 v6, 0, v6
	v_mul_f32_e32 v10, v2, v2
	v_max_f32_e32 v2, 0, v7
	v_mul_f32_e32 v7, v3, v3
	v_max_f32_e32 v3, 0, v8
	v_mul_f32_e32 v8, v4, v4
	v_max_f32_e32 v4, 0, v9
	v_mul_f32_e32 v2, v2, v2
	v_mul_f32_e32 v3, v3, v3
	v_mul_f32_e32 v4, v4, v4
	v_mul_f32_e32 v5, v5, v5
	s_andn2_b64 vcc, exec, s[38:39]
	v_mul_f32_e32 v6, v6, v6
	v_cvt_pk_bf16_f32 v2, v6, v2
	v_cvt_pk_bf16_f32 v3, v3, v4
	v_cvt_pk_bf16_f32 v4, v10, v7
	v_cvt_pk_bf16_f32 v5, v8, v5
	global_store_dwordx4 v[14:15], v[2:5], off offset:256
	s_cbranch_vccnz .LBB0_947
	s_andn2_b64 vcc, exec, s[0:1]
	s_cbranch_vccnz .LBB0_946
	s_barrier
	s_branch .LBB0_946
